# K-loop: counted lgkmcnt ladder at first consumers instead of lgkmcnt(0) at MFMA block head
# speedup vs baseline: 1.0100x; 1.0100x over previous
; #define PG8_STAGE(bufoff, gbase, voff) do { _Pragma("unroll") for (int _i = 0; _i < 2; ++_i) \
;         __builtin_amdgcn_global_load_lds((const unsigned*)((const char*)(gbase) + (voff)[_i]), (LAS unsigned*)(lds + (bufoff) + ldsw + _i * 8192), 16, 0, 0); } while (0)
; #define PG8_WAIT_V(n) asm volatile("s_waitcnt vmcnt(" #n ")" ::: "memory")
; #define PG8_WAIT_L(n) asm volatile("s_waitcnt lgkmcnt(" #n ")" ::: "memory")
; template <class Epi>
; __device__ __forceinline__ void gemm_phase(LAS unsigned char* lds, const Gemm g, const StaticOrder& S, const Epi& E) {
;     ...
;         const bool has_next = S.next(ui + 1, nxt);
;         const char* nA = has_next ? (const char*)g.A + (size_t)nxt.pm * tstepA : cA; const char* nB = has_next ? (const char*)g.Bt + (size_t)nxt.pn * tstepB : cB;
;         for (int t = 0; t < nt; t += 2) {
;             const bool last = (t == nt - 2);
;             const char* a1 = cA + (size_t)(t + 1) * kstep;
;             const char* a2 = last ? nA : cA + (size_t)(t + 2) * kstep; const char* b2 = last ? nB : cB + (size_t)(t + 2) * kstep;
;             const char* a3 = a2 + kstep; const char* b3 = b2 + kstep;
;             PG8_LDB(B0, 0, 0); PG8_SCHED; PG8_LDA(At, 0, 0); PG8_STAGE(PG8_SA(1, 1), a1 + hstepA, voffA);
;             PG8_WAIT_L(8); PG8_BAR; PG8_WAIT_L(0); PG8_MMA(0, 0, At, B0); PG8_BAR; PG8_SCHED;
;             PG8_LDB(B1, 0, 1); PG8_STAGE(PG8_SB(0, 0), b2, voffB);
;             PG8_BAR; PG8_WAIT_L(0); PG8_MMA(0, 1, At, B1); PG8_BAR;
;             PG8_LDA(At, 0, 1); PG8_STAGE(PG8_SA(0, 0), a2, voffA);
;             PG8_BAR; PG8_WAIT_L(0); PG8_MMA(1, 0, At, B0); PG8_BAR; PG8_SCHED;
;             PG8_STAGE(PG8_SB(0, 1), b2 + hstepB, voffB);
;             PG8_WAIT_V(6); PG8_BAR; PG8_MMA(1, 1, At, B1); PG8_BAR;
;             PG8_LDB(B0, 1, 0); PG8_SCHED; PG8_LDA(At, 1, 0); PG8_STAGE(PG8_SA(0, 1), a2 + hstepA, voffA);
;             PG8_WAIT_L(8); PG8_BAR; PG8_WAIT_L(0); PG8_MMA(0, 0, At, B0); PG8_BAR; PG8_SCHED;
;             PG8_LDB(B1, 1, 1); PG8_STAGE(PG8_SB(1, 0), b3, voffB);
;             PG8_BAR; PG8_WAIT_L(0); PG8_MMA(0, 1, At, B1); PG8_BAR;
;             PG8_LDA(At, 1, 1); PG8_STAGE(PG8_SA(1, 0), a3, voffA);
;             PG8_BAR; PG8_WAIT_L(0); PG8_MMA(1, 0, At, B0); PG8_BAR; PG8_SCHED;
;             PG8_STAGE(PG8_SB(1, 1), b3 + hstepB, voffB);
;             PG8_WAIT_V(6); PG8_BAR; PG8_MMA(1, 1, At, B1); PG8_BAR;
.LBB0_140:
	v_mov_b64_e32 v[0:1], 0x800
	s_ashr_i32 s15, s14, 31
	v_cmp_lt_i64_e32 vcc, s[16:17], v[0:1]
	s_lshl_b64 s[16:17], s[14:15], 20
	v_readlane_b32 s18, v252, 53
	v_readlane_b32 s19, v252, 54
	s_add_u32 s16, s18, s16
	s_addc_u32 s17, s19, s17
	s_and_b64 s[18:19], vcc, exec
	s_cselect_b32 s15, s17, s23
	s_cselect_b32 s49, s16, s22
	s_ashr_i32 s5, s4, 31
	s_lshl_b64 s[18:19], s[4:5], 20
	s_add_u32 s18, s34, s18
	s_addc_u32 s19, s35, s19
	s_and_b64 s[26:27], vcc, exec
	s_cselect_b32 s5, s19, s25
	s_cselect_b32 s50, s18, s24
	s_add_u32 s22, s22, 0x84000
	s_addc_u32 s23, s23, 0
	s_add_u32 s51, s24, 0x8000
	s_addc_u32 s52, s25, 0
	s_mov_b32 s54, -2
	s_add_u32 s24, s22, 0xfff84000
	s_addc_u32 s25, s23, -1
	s_cmp_eq_u32 s54, 28
	s_cselect_b32 s28, s49, s24
	s_cselect_b32 s29, s15, s25
	s_cselect_b32 s24, s50, s51
	s_cselect_b32 s25, s5, s52
	s_add_u32 s26, s28, 0x4000
	s_addc_u32 s27, s29, 0
	s_add_i32 s55, 0, 0x10000
	v_add_u32_e32 v148, s55, v134
	ds_read_b128 v[136:139], v148
	ds_read_b128 v[140:143], v148 offset:1024
	ds_read_b128 v[144:147], v148 offset:2048
	ds_read_b128 v[148:151], v148 offset:3072
	v_lshl_add_u64 v[188:189], s[22:23], 0, v[128:129]
	s_add_i32 m0, s37, 0xc000
	ds_read_b128 v[156:159], v135
	ds_read_b128 v[160:163], v135 offset:1024
	ds_read_b128 v[164:167], v135 offset:2048
	ds_read_b128 v[168:171], v135 offset:3072
	ds_read_b128 v[172:175], v135 offset:4096
	ds_read_b128 v[176:179], v135 offset:5120
	ds_read_b128 v[180:183], v135 offset:6144
	ds_read_b128 v[184:187], v135 offset:7168
	global_load_lds_dwordx4 v[188:189], off
	s_add_i32 m0, s37, 0xe000
	v_lshl_add_u64 v[188:189], s[22:23], 0, v[130:131]
	global_load_lds_dwordx4 v[188:189], off
	s_waitcnt lgkmcnt(8)
	s_barrier
	s_waitcnt lgkmcnt(7)
	v_mfma_f32_16x16x32_bf16 v[124:127], v[136:139], v[156:159], 0
	s_setprio 1
	v_mfma_f32_16x16x32_bf16 v[120:123], v[144:147], v[156:159], 0
	s_waitcnt lgkmcnt(5)
	v_mfma_f32_16x16x32_bf16 v[108:111], v[136:139], v[164:167], 0
	v_mfma_f32_16x16x32_bf16 v[104:107], v[144:147], v[164:167], 0
	s_waitcnt lgkmcnt(3)
	v_mfma_f32_16x16x32_bf16 v[92:95], v[136:139], v[172:175], 0
	v_mfma_f32_16x16x32_bf16 v[88:91], v[144:147], v[172:175], 0
	s_waitcnt lgkmcnt(1)
	v_mfma_f32_16x16x32_bf16 v[76:79], v[136:139], v[180:183], 0
	v_mfma_f32_16x16x32_bf16 v[72:75], v[144:147], v[180:183], 0
	v_mfma_f32_16x16x32_bf16 v[124:127], v[140:143], v[160:163], v[124:127]
	v_mfma_f32_16x16x32_bf16 v[120:123], v[148:151], v[160:163], v[120:123]
	v_mfma_f32_16x16x32_bf16 v[108:111], v[140:143], v[168:171], v[108:111]
	v_mfma_f32_16x16x32_bf16 v[104:107], v[148:151], v[168:171], v[104:107]
	v_mfma_f32_16x16x32_bf16 v[92:95], v[140:143], v[176:179], v[92:95]
	v_mfma_f32_16x16x32_bf16 v[88:91], v[148:151], v[176:179], v[88:91]
	s_waitcnt lgkmcnt(0)
	v_mfma_f32_16x16x32_bf16 v[76:79], v[140:143], v[184:187], v[76:79]
	s_setprio 0
	v_mfma_f32_16x16x32_bf16 v[72:75], v[148:151], v[184:187], v[72:75]
	s_barrier
	s_add_i32 s58, 0, 0x14000
	s_add_i32 s55, s55, s36
	v_add_u32_e32 v152, s58, v134
	v_lshl_add_u64 v[204:205], s[24:25], 0, v[128:129]
	s_mov_b32 m0, s55
	ds_read_b128 v[188:191], v152
	ds_read_b128 v[192:195], v152 offset:1024
	ds_read_b128 v[196:199], v152 offset:2048
	ds_read_b128 v[200:203], v152 offset:3072
	global_load_lds_dwordx4 v[204:205], off
	s_add_i32 m0, s55, 0x2000
	v_lshl_add_u64 v[204:205], s[24:25], 0, v[130:131]
	global_load_lds_dwordx4 v[204:205], off
	s_barrier
	s_waitcnt lgkmcnt(3)
	v_mfma_f32_16x16x32_bf16 v[116:119], v[188:191], v[156:159], 0
	s_setprio 1
	s_waitcnt lgkmcnt(1)
	v_mfma_f32_16x16x32_bf16 v[112:115], v[196:199], v[156:159], 0
	s_mov_b32 m0, s37
	v_lshl_add_u64 v[204:205], s[28:29], 0, v[128:129]
	v_mfma_f32_16x16x32_bf16 v[100:103], v[188:191], v[164:167], 0
	v_mfma_f32_16x16x32_bf16 v[96:99], v[196:199], v[164:167], 0
	v_mfma_f32_16x16x32_bf16 v[84:87], v[188:191], v[172:175], 0
	v_mfma_f32_16x16x32_bf16 v[80:83], v[196:199], v[172:175], 0
	v_mfma_f32_16x16x32_bf16 v[68:71], v[188:191], v[180:183], 0
	v_mfma_f32_16x16x32_bf16 v[64:67], v[196:199], v[180:183], 0
	v_mfma_f32_16x16x32_bf16 v[116:119], v[192:195], v[160:163], v[116:119]
	s_waitcnt lgkmcnt(0)
	v_mfma_f32_16x16x32_bf16 v[112:115], v[200:203], v[160:163], v[112:115]
	v_mfma_f32_16x16x32_bf16 v[100:103], v[192:195], v[168:171], v[100:103]
	v_mfma_f32_16x16x32_bf16 v[96:99], v[200:203], v[168:171], v[96:99]
	v_mfma_f32_16x16x32_bf16 v[84:87], v[192:195], v[176:179], v[84:87]
	v_mfma_f32_16x16x32_bf16 v[80:83], v[200:203], v[176:179], v[80:83]
	v_mfma_f32_16x16x32_bf16 v[68:71], v[192:195], v[184:187], v[68:71]
	s_setprio 0
	v_mfma_f32_16x16x32_bf16 v[64:67], v[200:203], v[184:187], v[64:67]
	s_barrier
	ds_read_b128 v[156:159], v135 offset:16384
	ds_read_b128 v[160:163], v135 offset:17408
	ds_read_b128 v[164:167], v135 offset:18432
	ds_read_b128 v[168:171], v135 offset:19456
	ds_read_b128 v[172:175], v135 offset:20480
	ds_read_b128 v[176:179], v135 offset:21504
	ds_read_b128 v[180:183], v135 offset:22528
	ds_read_b128 v[184:187], v135 offset:23552
	global_load_lds_dwordx4 v[204:205], off
	s_mov_b32 m0, s38
	v_lshl_add_u64 v[204:205], s[28:29], 0, v[130:131]
	global_load_lds_dwordx4 v[204:205], off
	s_barrier
; #define PG8_STAGE(bufoff, gbase, voff) do { _Pragma("unroll") for (int _i = 0; _i < 2; ++_i) \
;         __builtin_amdgcn_global_load_lds((const unsigned*)((const char*)(gbase) + (voff)[_i]), (LAS unsigned*)(lds + (bufoff) + ldsw + _i * 8192), 16, 0, 0); } while (0)
; #define PG8_LDA(dst, b, h) do { _Pragma("unroll") for (int m = 0; m < 4; ++m) _Pragma("unroll") for (int k = 0; k < 2; ++k) dst[m][k] = *(const LAS bf16x8*)(lds + PG8_SA(b, h) + aoff + m * 2048 + k * 1024); } while (0)
; #define PG8_LDB(dst, b, h) do { _Pragma("unroll") for (int n = 0; n < 2; ++n) _Pragma("unroll") for (int k = 0; k < 2; ++k) dst[n][k] = *(const LAS bf16x8*)(lds + PG8_SB(b, h) + boff + n * 2048 + k * 1024); } while (0)
; #define PG8_MMA(ai, bj, At, Bt) do { __builtin_amdgcn_s_setprio(1); _Pragma("unroll") for (int m = 0; m < 4; ++m) _Pragma("unroll") for (int n = 0; n < 2; ++n) _Pragma("unroll") for (int k = 0; k < 2; ++k) \
;         acc[ai][bj][m][n] = __builtin_amdgcn_mfma_f32_16x16x32_bf16(Bt[n][k], At[m][k], acc[ai][bj][m][n], 0, 0, 0); __builtin_amdgcn_s_setprio(0); } while (0)
; #define PG8_WAIT_V(n) asm volatile("s_waitcnt vmcnt(" #n ")" ::: "memory")
; #define PG8_WAIT_L(n) asm volatile("s_waitcnt lgkmcnt(" #n ")" ::: "memory")
; #define PG8_BAR __builtin_amdgcn_s_barrier()
; #define PG8_SCHED __builtin_amdgcn_sched_barrier(0)
; template <class Epi>
; __device__ __forceinline__ void gemm_phase(LAS unsigned char* lds, const Gemm g, const StaticOrder& S, const Epi& E) {
;     ...
;             PG8_BAR; PG8_WAIT_L(0); PG8_MMA(0, 1, At, B1); PG8_BAR;
;             PG8_LDA(At, 0, 1); PG8_STAGE(PG8_SA(0, 0), a2, voffA);
;             PG8_BAR; PG8_WAIT_L(0); PG8_MMA(1, 0, At, B0); PG8_BAR; PG8_SCHED;
;             PG8_STAGE(PG8_SB(0, 1), b2 + hstepB, voffB);
;             PG8_WAIT_V(6); PG8_BAR; PG8_MMA(1, 1, At, B1); PG8_BAR;
;             PG8_LDB(B0, 1, 0); PG8_SCHED; PG8_LDA(At, 1, 0); PG8_STAGE(PG8_SA(0, 1), a2 + hstepA, voffA);
;             PG8_WAIT_L(8); PG8_BAR; PG8_WAIT_L(0); PG8_MMA(0, 0, At, B0); PG8_BAR; PG8_SCHED;
;             PG8_LDB(B1, 1, 1); PG8_STAGE(PG8_SB(1, 0), b3, voffB);
;             PG8_BAR; PG8_WAIT_L(0); PG8_MMA(0, 1, At, B1); PG8_BAR;
	s_waitcnt lgkmcnt(7)
	v_mfma_f32_16x16x32_bf16 v[60:63], v[136:139], v[156:159], 0
	s_setprio 1
	v_mfma_f32_16x16x32_bf16 v[56:59], v[144:147], v[156:159], 0
	s_waitcnt lgkmcnt(5)
	v_mfma_f32_16x16x32_bf16 v[44:47], v[136:139], v[164:167], 0
	v_mfma_f32_16x16x32_bf16 v[40:43], v[144:147], v[164:167], 0
	s_waitcnt lgkmcnt(3)
	v_mfma_f32_16x16x32_bf16 v[28:31], v[136:139], v[172:175], 0
	v_mfma_f32_16x16x32_bf16 v[24:27], v[144:147], v[172:175], 0
	s_waitcnt lgkmcnt(1)
	v_mfma_f32_16x16x32_bf16 v[12:15], v[136:139], v[180:183], 0
	v_mfma_f32_16x16x32_bf16 v[8:11], v[144:147], v[180:183], 0
	v_mfma_f32_16x16x32_bf16 v[60:63], v[140:143], v[160:163], v[60:63]
	v_mfma_f32_16x16x32_bf16 v[56:59], v[148:151], v[160:163], v[56:59]
	v_mfma_f32_16x16x32_bf16 v[44:47], v[140:143], v[168:171], v[44:47]
	v_mfma_f32_16x16x32_bf16 v[40:43], v[148:151], v[168:171], v[40:43]
	v_mfma_f32_16x16x32_bf16 v[28:31], v[140:143], v[176:179], v[28:31]
	v_mfma_f32_16x16x32_bf16 v[24:27], v[148:151], v[176:179], v[24:27]
	s_waitcnt lgkmcnt(0)
	v_mfma_f32_16x16x32_bf16 v[12:15], v[140:143], v[184:187], v[12:15]
	s_setprio 0
	v_mfma_f32_16x16x32_bf16 v[8:11], v[148:151], v[184:187], v[8:11]
	s_barrier
	s_add_u32 s56, s24, 0x80000
	s_addc_u32 s57, s25, 0
	s_add_i32 s55, s58, s36
	s_mov_b32 m0, s55
	v_lshl_add_u64 v[136:137], s[56:57], 0, v[128:129]
	global_load_lds_dwordx4 v[136:137], off
	s_add_i32 m0, s55, 0x2000
	v_lshl_add_u64 v[136:137], s[56:57], 0, v[130:131]
	global_load_lds_dwordx4 v[136:137], off
	s_waitcnt vmcnt(6)
	s_barrier
	v_mfma_f32_16x16x32_bf16 v[52:55], v[188:191], v[156:159], 0
	s_setprio 1
	v_mfma_f32_16x16x32_bf16 v[48:51], v[196:199], v[156:159], 0
	s_add_i32 s55, 0, 0x18000
	v_add_u32_e32 v148, s55, v134
	v_mfma_f32_16x16x32_bf16 v[36:39], v[188:191], v[164:167], 0
	v_mfma_f32_16x16x32_bf16 v[32:35], v[196:199], v[164:167], 0
	v_mfma_f32_16x16x32_bf16 v[20:23], v[188:191], v[172:175], 0
	v_mfma_f32_16x16x32_bf16 v[16:19], v[196:199], v[172:175], 0
	v_mfma_f32_16x16x32_bf16 v[4:7], v[188:191], v[180:183], 0
	v_mfma_f32_16x16x32_bf16 v[0:3], v[196:199], v[180:183], 0
	v_mfma_f32_16x16x32_bf16 v[52:55], v[192:195], v[160:163], v[52:55]
	v_mfma_f32_16x16x32_bf16 v[48:51], v[200:203], v[160:163], v[48:51]
	v_mfma_f32_16x16x32_bf16 v[36:39], v[192:195], v[168:171], v[36:39]
	v_mfma_f32_16x16x32_bf16 v[32:35], v[200:203], v[168:171], v[32:35]
	v_mfma_f32_16x16x32_bf16 v[20:23], v[192:195], v[176:179], v[20:23]
	v_mfma_f32_16x16x32_bf16 v[16:19], v[200:203], v[176:179], v[16:19]
	v_mfma_f32_16x16x32_bf16 v[4:7], v[192:195], v[184:187], v[4:7]
	s_setprio 0
	v_mfma_f32_16x16x32_bf16 v[0:3], v[200:203], v[184:187], v[0:3]
	s_barrier
	ds_read_b128 v[136:139], v148
	ds_read_b128 v[140:143], v148 offset:1024
	ds_read_b128 v[144:147], v148 offset:2048
	ds_read_b128 v[148:151], v148 offset:3072
	s_add_u32 s28, s28, 0x80000
	s_addc_u32 s29, s29, 0
	s_mov_b32 m0, s39
	v_lshl_add_u64 v[188:189], s[28:29], 0, v[128:129]
	ds_read_b128 v[156:159], v135 offset:32768
	ds_read_b128 v[160:163], v135 offset:33792
	ds_read_b128 v[164:167], v135 offset:34816
	ds_read_b128 v[168:171], v135 offset:35840
	ds_read_b128 v[172:175], v135 offset:36864
	ds_read_b128 v[176:179], v135 offset:37888
	ds_read_b128 v[180:183], v135 offset:38912
	ds_read_b128 v[184:187], v135 offset:39936
	global_load_lds_dwordx4 v[188:189], off
	s_mov_b32 m0, s40
	v_lshl_add_u64 v[188:189], s[28:29], 0, v[130:131]
	global_load_lds_dwordx4 v[188:189], off
	s_waitcnt lgkmcnt(8)
	s_barrier
	s_waitcnt lgkmcnt(7)
	v_mfma_f32_16x16x32_bf16 v[124:127], v[136:139], v[156:159], v[124:127]
	s_setprio 1
	v_mfma_f32_16x16x32_bf16 v[120:123], v[144:147], v[156:159], v[120:123]
	s_waitcnt lgkmcnt(5)
	v_mfma_f32_16x16x32_bf16 v[108:111], v[136:139], v[164:167], v[108:111]
	v_mfma_f32_16x16x32_bf16 v[104:107], v[144:147], v[164:167], v[104:107]
	s_waitcnt lgkmcnt(3)
	v_mfma_f32_16x16x32_bf16 v[92:95], v[136:139], v[172:175], v[92:95]
	v_mfma_f32_16x16x32_bf16 v[88:91], v[144:147], v[172:175], v[88:91]
	s_waitcnt lgkmcnt(1)
	v_mfma_f32_16x16x32_bf16 v[76:79], v[136:139], v[180:183], v[76:79]
	v_mfma_f32_16x16x32_bf16 v[72:75], v[144:147], v[180:183], v[72:75]
	v_mfma_f32_16x16x32_bf16 v[124:127], v[140:143], v[160:163], v[124:127]
	v_mfma_f32_16x16x32_bf16 v[120:123], v[148:151], v[160:163], v[120:123]
	v_mfma_f32_16x16x32_bf16 v[108:111], v[140:143], v[168:171], v[108:111]
	v_mfma_f32_16x16x32_bf16 v[104:107], v[148:151], v[168:171], v[104:107]
	v_mfma_f32_16x16x32_bf16 v[92:95], v[140:143], v[176:179], v[92:95]
	v_mfma_f32_16x16x32_bf16 v[88:91], v[148:151], v[176:179], v[88:91]
	s_waitcnt lgkmcnt(0)
	v_mfma_f32_16x16x32_bf16 v[76:79], v[140:143], v[184:187], v[76:79]
	s_setprio 0
	v_mfma_f32_16x16x32_bf16 v[72:75], v[148:151], v[184:187], v[72:75]
	s_barrier
	s_add_i32 s56, 0, 0x1c000
	s_add_u32 s28, s24, 0x4000
	s_addc_u32 s29, s25, 0
	s_add_i32 s55, s55, s36
	v_add_u32_e32 v152, s56, v134
	v_lshl_add_u64 v[204:205], s[28:29], 0, v[128:129]
	s_mov_b32 m0, s55
	ds_read_b128 v[188:191], v152
	ds_read_b128 v[192:195], v152 offset:1024
	ds_read_b128 v[196:199], v152 offset:2048
	ds_read_b128 v[200:203], v152 offset:3072
	global_load_lds_dwordx4 v[204:205], off
	s_add_i32 m0, s55, 0x2000
	v_lshl_add_u64 v[204:205], s[28:29], 0, v[130:131]
	global_load_lds_dwordx4 v[204:205], off
	s_barrier
; #define PG8_STAGE(bufoff, gbase, voff) do { _Pragma("unroll") for (int _i = 0; _i < 2; ++_i) \
;         __builtin_amdgcn_global_load_lds((const unsigned*)((const char*)(gbase) + (voff)[_i]), (LAS unsigned*)(lds + (bufoff) + ldsw + _i * 8192), 16, 0, 0); } while (0)
; #define PG8_LDA(dst, b, h) do { _Pragma("unroll") for (int m = 0; m < 4; ++m) _Pragma("unroll") for (int k = 0; k < 2; ++k) dst[m][k] = *(const LAS bf16x8*)(lds + PG8_SA(b, h) + aoff + m * 2048 + k * 1024); } while (0)
; #define PG8_LDB(dst, b, h) do { _Pragma("unroll") for (int n = 0; n < 2; ++n) _Pragma("unroll") for (int k = 0; k < 2; ++k) dst[n][k] = *(const LAS bf16x8*)(lds + PG8_SB(b, h) + boff + n * 2048 + k * 1024); } while (0)
; #define PG8_MMA(ai, bj, At, Bt) do { __builtin_amdgcn_s_setprio(1); _Pragma("unroll") for (int m = 0; m < 4; ++m) _Pragma("unroll") for (int n = 0; n < 2; ++n) _Pragma("unroll") for (int k = 0; k < 2; ++k) \
;         acc[ai][bj][m][n] = __builtin_amdgcn_mfma_f32_16x16x32_bf16(Bt[n][k], At[m][k], acc[ai][bj][m][n], 0, 0, 0); __builtin_amdgcn_s_setprio(0); } while (0)
; #define PG8_WAIT_V(n) asm volatile("s_waitcnt vmcnt(" #n ")" ::: "memory")
; #define PG8_WAIT_L(n) asm volatile("s_waitcnt lgkmcnt(" #n ")" ::: "memory")
; #define PG8_BAR __builtin_amdgcn_s_barrier()
; #define PG8_SCHED __builtin_amdgcn_sched_barrier(0)
; template <class Epi>
; __device__ __forceinline__ void gemm_phase(LAS unsigned char* lds, const Gemm g, const StaticOrder& S, const Epi& E) {
;     ...
;             PG8_WAIT_L(8); PG8_BAR; PG8_WAIT_L(0); PG8_MMA(0, 0, At, B0); PG8_BAR; PG8_SCHED;
;             PG8_LDB(B1, 1, 1); PG8_STAGE(PG8_SB(1, 0), b3, voffB);
;             PG8_BAR; PG8_WAIT_L(0); PG8_MMA(0, 1, At, B1); PG8_BAR;
;             PG8_LDA(At, 1, 1); PG8_STAGE(PG8_SA(1, 0), a3, voffA);
;             PG8_BAR; PG8_WAIT_L(0); PG8_MMA(1, 0, At, B0); PG8_BAR; PG8_SCHED;
;             PG8_STAGE(PG8_SB(1, 1), b3 + hstepB, voffB);
;             PG8_WAIT_V(6); PG8_BAR; PG8_MMA(1, 1, At, B1); PG8_BAR;
	s_waitcnt lgkmcnt(3)
	v_mfma_f32_16x16x32_bf16 v[116:119], v[188:191], v[156:159], v[116:119]
	s_setprio 1
	s_waitcnt lgkmcnt(1)
	v_mfma_f32_16x16x32_bf16 v[112:115], v[196:199], v[156:159], v[112:115]
	s_mov_b32 m0, s43
	v_lshl_add_u64 v[204:205], s[26:27], 0, v[128:129]
	v_mfma_f32_16x16x32_bf16 v[100:103], v[188:191], v[164:167], v[100:103]
	v_mfma_f32_16x16x32_bf16 v[96:99], v[196:199], v[164:167], v[96:99]
	v_mfma_f32_16x16x32_bf16 v[84:87], v[188:191], v[172:175], v[84:87]
	v_mfma_f32_16x16x32_bf16 v[80:83], v[196:199], v[172:175], v[80:83]
	v_mfma_f32_16x16x32_bf16 v[68:71], v[188:191], v[180:183], v[68:71]
	v_mfma_f32_16x16x32_bf16 v[64:67], v[196:199], v[180:183], v[64:67]
	v_mfma_f32_16x16x32_bf16 v[116:119], v[192:195], v[160:163], v[116:119]
	s_waitcnt lgkmcnt(0)
	v_mfma_f32_16x16x32_bf16 v[112:115], v[200:203], v[160:163], v[112:115]
	v_mfma_f32_16x16x32_bf16 v[100:103], v[192:195], v[168:171], v[100:103]
	v_mfma_f32_16x16x32_bf16 v[96:99], v[200:203], v[168:171], v[96:99]
	v_mfma_f32_16x16x32_bf16 v[84:87], v[192:195], v[176:179], v[84:87]
	v_mfma_f32_16x16x32_bf16 v[80:83], v[200:203], v[176:179], v[80:83]
	v_mfma_f32_16x16x32_bf16 v[68:71], v[192:195], v[184:187], v[68:71]
	s_setprio 0
	v_mfma_f32_16x16x32_bf16 v[64:67], v[200:203], v[184:187], v[64:67]
	s_barrier
	ds_read_b128 v[156:159], v135 offset:49152
	ds_read_b128 v[160:163], v135 offset:50176
	ds_read_b128 v[164:167], v135 offset:51200
	ds_read_b128 v[168:171], v135 offset:52224
	ds_read_b128 v[172:175], v135 offset:53248
	ds_read_b128 v[176:179], v135 offset:54272
	ds_read_b128 v[180:183], v135 offset:55296
	ds_read_b128 v[184:187], v135 offset:56320
	global_load_lds_dwordx4 v[204:205], off
	s_mov_b32 m0, s44
	v_lshl_add_u64 v[204:205], s[26:27], 0, v[130:131]
	global_load_lds_dwordx4 v[204:205], off
	s_barrier
	s_waitcnt lgkmcnt(7)
	v_mfma_f32_16x16x32_bf16 v[60:63], v[136:139], v[156:159], v[60:63]
	s_setprio 1
	v_mfma_f32_16x16x32_bf16 v[56:59], v[144:147], v[156:159], v[56:59]
	s_waitcnt lgkmcnt(5)
	v_mfma_f32_16x16x32_bf16 v[44:47], v[136:139], v[164:167], v[44:47]
	v_mfma_f32_16x16x32_bf16 v[40:43], v[144:147], v[164:167], v[40:43]
	s_waitcnt lgkmcnt(3)
	v_mfma_f32_16x16x32_bf16 v[28:31], v[136:139], v[172:175], v[28:31]
	v_mfma_f32_16x16x32_bf16 v[24:27], v[144:147], v[172:175], v[24:27]
	s_waitcnt lgkmcnt(1)
	v_mfma_f32_16x16x32_bf16 v[12:15], v[136:139], v[180:183], v[12:15]
	v_mfma_f32_16x16x32_bf16 v[8:11], v[144:147], v[180:183], v[8:11]
	v_mfma_f32_16x16x32_bf16 v[60:63], v[140:143], v[160:163], v[60:63]
	v_mfma_f32_16x16x32_bf16 v[56:59], v[148:151], v[160:163], v[56:59]
	v_mfma_f32_16x16x32_bf16 v[44:47], v[140:143], v[168:171], v[44:47]
	v_mfma_f32_16x16x32_bf16 v[40:43], v[148:151], v[168:171], v[40:43]
	v_mfma_f32_16x16x32_bf16 v[28:31], v[140:143], v[176:179], v[28:31]
	v_mfma_f32_16x16x32_bf16 v[24:27], v[148:151], v[176:179], v[24:27]
	s_waitcnt lgkmcnt(0)
	v_mfma_f32_16x16x32_bf16 v[12:15], v[140:143], v[184:187], v[12:15]
	s_setprio 0
	v_mfma_f32_16x16x32_bf16 v[8:11], v[148:151], v[184:187], v[8:11]
	s_barrier
	s_add_u32 s24, s24, 0x84000
	s_addc_u32 s25, s25, 0
	s_add_i32 s26, s56, s36
	s_mov_b32 m0, s26
	v_lshl_add_u64 v[136:137], s[24:25], 0, v[128:129]
	global_load_lds_dwordx4 v[136:137], off
	s_add_i32 m0, s26, 0x2000
	v_lshl_add_u64 v[136:137], s[24:25], 0, v[130:131]
	global_load_lds_dwordx4 v[136:137], off
	s_waitcnt vmcnt(6)
	s_barrier
	v_mfma_f32_16x16x32_bf16 v[52:55], v[188:191], v[156:159], v[52:55]
	s_setprio 1
	v_mfma_f32_16x16x32_bf16 v[48:51], v[196:199], v[156:159], v[48:51]
	s_add_i32 s54, s54, 2
	s_add_u32 s22, s22, 0x8000
	s_addc_u32 s23, s23, 0
	s_add_u32 s51, s51, 0x8000
	s_addc_u32 s52, s52, 0
	v_mfma_f32_16x16x32_bf16 v[36:39], v[188:191], v[164:167], v[36:39]
	v_mfma_f32_16x16x32_bf16 v[32:35], v[196:199], v[164:167], v[32:35]
	v_mfma_f32_16x16x32_bf16 v[20:23], v[188:191], v[172:175], v[20:23]
	v_mfma_f32_16x16x32_bf16 v[16:19], v[196:199], v[172:175], v[16:19]
	v_mfma_f32_16x16x32_bf16 v[4:7], v[188:191], v[180:183], v[4:7]
	v_mfma_f32_16x16x32_bf16 v[0:3], v[196:199], v[180:183], v[0:3]
	v_mfma_f32_16x16x32_bf16 v[52:55], v[192:195], v[160:163], v[52:55]
	v_mfma_f32_16x16x32_bf16 v[48:51], v[200:203], v[160:163], v[48:51]
	v_mfma_f32_16x16x32_bf16 v[36:39], v[192:195], v[168:171], v[36:39]
	v_mfma_f32_16x16x32_bf16 v[32:35], v[200:203], v[168:171], v[32:35]
	v_mfma_f32_16x16x32_bf16 v[20:23], v[192:195], v[176:179], v[20:23]
	v_mfma_f32_16x16x32_bf16 v[16:19], v[200:203], v[176:179], v[16:19]
	v_mfma_f32_16x16x32_bf16 v[4:7], v[192:195], v[184:187], v[4:7]
	s_cmp_gt_u32 s54, 29
	s_setprio 0
	v_mfma_f32_16x16x32_bf16 v[0:3], v[200:203], v[184:187], v[0:3]
	s_barrier
	s_cbranch_scc0 .LBB0_141
	s_branch .Lpeel_done_141
; #define PG8_STAGE(bufoff, gbase, voff) do { _Pragma("unroll") for (int _i = 0; _i < 2; ++_i) \
;         __builtin_amdgcn_global_load_lds((const unsigned*)((const char*)(gbase) + (voff)[_i]), (LAS unsigned*)(lds + (bufoff) + ldsw + _i * 8192), 16, 0, 0); } while (0)
; #define PG8_LDA(dst, b, h) do { _Pragma("unroll") for (int m = 0; m < 4; ++m) _Pragma("unroll") for (int k = 0; k < 2; ++k) dst[m][k] = *(const LAS bf16x8*)(lds + PG8_SA(b, h) + aoff + m * 2048 + k * 1024); } while (0)
; #define PG8_LDB(dst, b, h) do { _Pragma("unroll") for (int n = 0; n < 2; ++n) _Pragma("unroll") for (int k = 0; k < 2; ++k) dst[n][k] = *(const LAS bf16x8*)(lds + PG8_SB(b, h) + boff + n * 2048 + k * 1024); } while (0)
; #define PG8_WAIT_V(n) asm volatile("s_waitcnt vmcnt(" #n ")" ::: "memory")
; #define PG8_WAIT_L(n) asm volatile("s_waitcnt lgkmcnt(" #n ")" ::: "memory")
; #define PG8_BAR __builtin_amdgcn_s_barrier()
; template <class Epi>
; __device__ __forceinline__ void gemm_phase(LAS unsigned char* lds, const Gemm g, const StaticOrder& S, const Epi& E) {
;     ...
;         for (int t = 0; t < nt; t += 2) {
;             const bool last = (t == nt - 2);
;             const char* a1 = cA + (size_t)(t + 1) * kstep;
;             const char* a2 = last ? nA : cA + (size_t)(t + 2) * kstep; const char* b2 = last ? nB : cB + (size_t)(t + 2) * kstep;
;             const char* a3 = a2 + kstep; const char* b3 = b2 + kstep;
;             PG8_LDB(B0, 0, 0); PG8_SCHED; PG8_LDA(At, 0, 0); PG8_STAGE(PG8_SA(1, 1), a1 + hstepA, voffA);
;             PG8_WAIT_L(8); PG8_BAR; PG8_WAIT_L(0); PG8_MMA(0, 0, At, B0); PG8_BAR; PG8_SCHED;
;             PG8_LDB(B1, 0, 1); PG8_STAGE(PG8_SB(0, 0), b2, voffB);
;             PG8_BAR; PG8_WAIT_L(0); PG8_MMA(0, 1, At, B1); PG8_BAR;
;             PG8_LDA(At, 0, 1); PG8_STAGE(PG8_SA(0, 0), a2, voffA);
;             PG8_BAR; PG8_WAIT_L(0); PG8_MMA(1, 0, At, B0); PG8_BAR; PG8_SCHED;
;             PG8_STAGE(PG8_SB(0, 1), b2 + hstepB, voffB);
;             PG8_WAIT_V(6); PG8_BAR; PG8_MMA(1, 1, At, B1); PG8_BAR;
;             PG8_LDB(B0, 1, 0); PG8_SCHED; PG8_LDA(At, 1, 0); PG8_STAGE(PG8_SA(0, 1), a2 + hstepA, voffA);
;             PG8_WAIT_L(8); PG8_BAR; PG8_WAIT_L(0); PG8_MMA(0, 0, At, B0); PG8_BAR; PG8_SCHED;
;             PG8_LDB(B1, 1, 1); PG8_STAGE(PG8_SB(1, 0), b3, voffB);
;             PG8_BAR; PG8_WAIT_L(0); PG8_MMA(0, 1, At, B1); PG8_BAR;
.LBB0_141:
	s_add_u32 s24, s22, 0xfff84000
	s_addc_u32 s25, s23, -1
	s_cmp_eq_u32 s54, 28
	s_cselect_b32 s28, s49, s24
	s_cselect_b32 s29, s15, s25
	s_cselect_b32 s24, s50, s51
	s_cselect_b32 s25, s5, s52
	s_add_u32 s26, s28, 0x4000
	s_addc_u32 s27, s29, 0
	s_add_i32 s55, 0, 0x10000
	v_add_u32_e32 v148, s55, v134
	ds_read_b128 v[136:139], v148
	ds_read_b128 v[140:143], v148 offset:1024
	ds_read_b128 v[144:147], v148 offset:2048
	ds_read_b128 v[148:151], v148 offset:3072
	v_lshl_add_u64 v[188:189], s[22:23], 0, v[128:129]
	s_add_i32 m0, s37, 0xc000
	ds_read_b128 v[156:159], v135
	ds_read_b128 v[160:163], v135 offset:1024
	ds_read_b128 v[164:167], v135 offset:2048
	ds_read_b128 v[168:171], v135 offset:3072
	ds_read_b128 v[172:175], v135 offset:4096
	ds_read_b128 v[176:179], v135 offset:5120
	ds_read_b128 v[180:183], v135 offset:6144
	ds_read_b128 v[184:187], v135 offset:7168
	global_load_lds_dwordx4 v[188:189], off
	s_add_i32 m0, s37, 0xe000
	v_lshl_add_u64 v[188:189], s[22:23], 0, v[130:131]
	global_load_lds_dwordx4 v[188:189], off
	s_waitcnt lgkmcnt(8)
	s_barrier
	s_waitcnt lgkmcnt(7)
	v_mfma_f32_16x16x32_bf16 v[124:127], v[136:139], v[156:159], v[124:127]
	s_setprio 1
	v_mfma_f32_16x16x32_bf16 v[120:123], v[144:147], v[156:159], v[120:123]
	s_waitcnt lgkmcnt(5)
	v_mfma_f32_16x16x32_bf16 v[108:111], v[136:139], v[164:167], v[108:111]
	v_mfma_f32_16x16x32_bf16 v[104:107], v[144:147], v[164:167], v[104:107]
	s_waitcnt lgkmcnt(3)
	v_mfma_f32_16x16x32_bf16 v[92:95], v[136:139], v[172:175], v[92:95]
	v_mfma_f32_16x16x32_bf16 v[88:91], v[144:147], v[172:175], v[88:91]
	s_waitcnt lgkmcnt(1)
	v_mfma_f32_16x16x32_bf16 v[76:79], v[136:139], v[180:183], v[76:79]
	v_mfma_f32_16x16x32_bf16 v[72:75], v[144:147], v[180:183], v[72:75]
	v_mfma_f32_16x16x32_bf16 v[124:127], v[140:143], v[160:163], v[124:127]
	v_mfma_f32_16x16x32_bf16 v[120:123], v[148:151], v[160:163], v[120:123]
	v_mfma_f32_16x16x32_bf16 v[108:111], v[140:143], v[168:171], v[108:111]
	v_mfma_f32_16x16x32_bf16 v[104:107], v[148:151], v[168:171], v[104:107]
	v_mfma_f32_16x16x32_bf16 v[92:95], v[140:143], v[176:179], v[92:95]
	v_mfma_f32_16x16x32_bf16 v[88:91], v[148:151], v[176:179], v[88:91]
	s_waitcnt lgkmcnt(0)
	v_mfma_f32_16x16x32_bf16 v[76:79], v[140:143], v[184:187], v[76:79]
	s_setprio 0
	v_mfma_f32_16x16x32_bf16 v[72:75], v[148:151], v[184:187], v[72:75]
	s_barrier
	s_add_i32 s58, 0, 0x14000
	s_add_i32 s55, s55, s36
	v_add_u32_e32 v152, s58, v134
	v_lshl_add_u64 v[204:205], s[24:25], 0, v[128:129]
	s_mov_b32 m0, s55
	ds_read_b128 v[188:191], v152
	ds_read_b128 v[192:195], v152 offset:1024
	ds_read_b128 v[196:199], v152 offset:2048
	ds_read_b128 v[200:203], v152 offset:3072
	global_load_lds_dwordx4 v[204:205], off
	s_add_i32 m0, s55, 0x2000
	v_lshl_add_u64 v[204:205], s[24:25], 0, v[130:131]
	global_load_lds_dwordx4 v[204:205], off
	s_barrier
	s_waitcnt lgkmcnt(3)
	v_mfma_f32_16x16x32_bf16 v[116:119], v[188:191], v[156:159], v[116:119]
	s_setprio 1
	s_waitcnt lgkmcnt(1)
	v_mfma_f32_16x16x32_bf16 v[112:115], v[196:199], v[156:159], v[112:115]
	s_mov_b32 m0, s37
	v_lshl_add_u64 v[204:205], s[28:29], 0, v[128:129]
	v_mfma_f32_16x16x32_bf16 v[100:103], v[188:191], v[164:167], v[100:103]
	v_mfma_f32_16x16x32_bf16 v[96:99], v[196:199], v[164:167], v[96:99]
	v_mfma_f32_16x16x32_bf16 v[84:87], v[188:191], v[172:175], v[84:87]
	v_mfma_f32_16x16x32_bf16 v[80:83], v[196:199], v[172:175], v[80:83]
	v_mfma_f32_16x16x32_bf16 v[68:71], v[188:191], v[180:183], v[68:71]
	v_mfma_f32_16x16x32_bf16 v[64:67], v[196:199], v[180:183], v[64:67]
	v_mfma_f32_16x16x32_bf16 v[116:119], v[192:195], v[160:163], v[116:119]
	s_waitcnt lgkmcnt(0)
	v_mfma_f32_16x16x32_bf16 v[112:115], v[200:203], v[160:163], v[112:115]
	v_mfma_f32_16x16x32_bf16 v[100:103], v[192:195], v[168:171], v[100:103]
	v_mfma_f32_16x16x32_bf16 v[96:99], v[200:203], v[168:171], v[96:99]
	v_mfma_f32_16x16x32_bf16 v[84:87], v[192:195], v[176:179], v[84:87]
	v_mfma_f32_16x16x32_bf16 v[80:83], v[200:203], v[176:179], v[80:83]
	v_mfma_f32_16x16x32_bf16 v[68:71], v[192:195], v[184:187], v[68:71]
	s_setprio 0
	v_mfma_f32_16x16x32_bf16 v[64:67], v[200:203], v[184:187], v[64:67]
	s_barrier
	ds_read_b128 v[156:159], v135 offset:16384
	ds_read_b128 v[160:163], v135 offset:17408
	ds_read_b128 v[164:167], v135 offset:18432
	ds_read_b128 v[168:171], v135 offset:19456
	ds_read_b128 v[172:175], v135 offset:20480
	ds_read_b128 v[176:179], v135 offset:21504
	ds_read_b128 v[180:183], v135 offset:22528
	ds_read_b128 v[184:187], v135 offset:23552
	global_load_lds_dwordx4 v[204:205], off
	s_mov_b32 m0, s38
	v_lshl_add_u64 v[204:205], s[28:29], 0, v[130:131]
	global_load_lds_dwordx4 v[204:205], off
	s_barrier
	s_waitcnt lgkmcnt(7)
	v_mfma_f32_16x16x32_bf16 v[60:63], v[136:139], v[156:159], v[60:63]
	s_setprio 1
	v_mfma_f32_16x16x32_bf16 v[56:59], v[144:147], v[156:159], v[56:59]
	s_waitcnt lgkmcnt(5)
	v_mfma_f32_16x16x32_bf16 v[44:47], v[136:139], v[164:167], v[44:47]
	v_mfma_f32_16x16x32_bf16 v[40:43], v[144:147], v[164:167], v[40:43]
	s_waitcnt lgkmcnt(3)
	v_mfma_f32_16x16x32_bf16 v[28:31], v[136:139], v[172:175], v[28:31]
	v_mfma_f32_16x16x32_bf16 v[24:27], v[144:147], v[172:175], v[24:27]
	s_waitcnt lgkmcnt(1)
	v_mfma_f32_16x16x32_bf16 v[12:15], v[136:139], v[180:183], v[12:15]
	v_mfma_f32_16x16x32_bf16 v[8:11], v[144:147], v[180:183], v[8:11]
	v_mfma_f32_16x16x32_bf16 v[60:63], v[140:143], v[160:163], v[60:63]
	v_mfma_f32_16x16x32_bf16 v[56:59], v[148:151], v[160:163], v[56:59]
	v_mfma_f32_16x16x32_bf16 v[44:47], v[140:143], v[168:171], v[44:47]
	v_mfma_f32_16x16x32_bf16 v[40:43], v[148:151], v[168:171], v[40:43]
	v_mfma_f32_16x16x32_bf16 v[28:31], v[140:143], v[176:179], v[28:31]
	v_mfma_f32_16x16x32_bf16 v[24:27], v[148:151], v[176:179], v[24:27]
	s_waitcnt lgkmcnt(0)
	v_mfma_f32_16x16x32_bf16 v[12:15], v[140:143], v[184:187], v[12:15]
	s_setprio 0
	v_mfma_f32_16x16x32_bf16 v[8:11], v[148:151], v[184:187], v[8:11]
	s_barrier
; #define PG8_STAGE(bufoff, gbase, voff) do { _Pragma("unroll") for (int _i = 0; _i < 2; ++_i) \
;         __builtin_amdgcn_global_load_lds((const unsigned*)((const char*)(gbase) + (voff)[_i]), (LAS unsigned*)(lds + (bufoff) + ldsw + _i * 8192), 16, 0, 0); } while (0)
; #define PG8_LDA(dst, b, h) do { _Pragma("unroll") for (int m = 0; m < 4; ++m) _Pragma("unroll") for (int k = 0; k < 2; ++k) dst[m][k] = *(const LAS bf16x8*)(lds + PG8_SA(b, h) + aoff + m * 2048 + k * 1024); } while (0)
; #define PG8_LDB(dst, b, h) do { _Pragma("unroll") for (int n = 0; n < 2; ++n) _Pragma("unroll") for (int k = 0; k < 2; ++k) dst[n][k] = *(const LAS bf16x8*)(lds + PG8_SB(b, h) + boff + n * 2048 + k * 1024); } while (0)
; #define PG8_MMA(ai, bj, At, Bt) do { __builtin_amdgcn_s_setprio(1); _Pragma("unroll") for (int m = 0; m < 4; ++m) _Pragma("unroll") for (int n = 0; n < 2; ++n) _Pragma("unroll") for (int k = 0; k < 2; ++k) \
;         acc[ai][bj][m][n] = __builtin_amdgcn_mfma_f32_16x16x32_bf16(Bt[n][k], At[m][k], acc[ai][bj][m][n], 0, 0, 0); __builtin_amdgcn_s_setprio(0); } while (0)
; #define PG8_WAIT_V(n) asm volatile("s_waitcnt vmcnt(" #n ")" ::: "memory")
; #define PG8_WAIT_L(n) asm volatile("s_waitcnt lgkmcnt(" #n ")" ::: "memory")
; #define PG8_BAR __builtin_amdgcn_s_barrier()
; #define PG8_SCHED __builtin_amdgcn_sched_barrier(0)
; template <class Epi>
; __device__ __forceinline__ void gemm_phase(LAS unsigned char* lds, const Gemm g, const StaticOrder& S, const Epi& E) {
;     ...
;             PG8_WAIT_V(6); PG8_BAR; PG8_MMA(1, 1, At, B1); PG8_BAR;
;             PG8_LDB(B0, 1, 0); PG8_SCHED; PG8_LDA(At, 1, 0); PG8_STAGE(PG8_SA(0, 1), a2 + hstepA, voffA);
;             PG8_WAIT_L(8); PG8_BAR; PG8_WAIT_L(0); PG8_MMA(0, 0, At, B0); PG8_BAR; PG8_SCHED;
;             PG8_LDB(B1, 1, 1); PG8_STAGE(PG8_SB(1, 0), b3, voffB);
;             PG8_BAR; PG8_WAIT_L(0); PG8_MMA(0, 1, At, B1); PG8_BAR;
	s_add_u32 s56, s24, 0x80000
	s_addc_u32 s57, s25, 0
	s_add_i32 s55, s58, s36
	s_mov_b32 m0, s55
	v_lshl_add_u64 v[136:137], s[56:57], 0, v[128:129]
	global_load_lds_dwordx4 v[136:137], off
	s_add_i32 m0, s55, 0x2000
	v_lshl_add_u64 v[136:137], s[56:57], 0, v[130:131]
	global_load_lds_dwordx4 v[136:137], off
	s_waitcnt vmcnt(6)
	s_barrier
	v_mfma_f32_16x16x32_bf16 v[52:55], v[188:191], v[156:159], v[52:55]
	s_setprio 1
	v_mfma_f32_16x16x32_bf16 v[48:51], v[196:199], v[156:159], v[48:51]
	s_add_i32 s55, 0, 0x18000
	v_add_u32_e32 v148, s55, v134
	v_mfma_f32_16x16x32_bf16 v[36:39], v[188:191], v[164:167], v[36:39]
	v_mfma_f32_16x16x32_bf16 v[32:35], v[196:199], v[164:167], v[32:35]
	v_mfma_f32_16x16x32_bf16 v[20:23], v[188:191], v[172:175], v[20:23]
	v_mfma_f32_16x16x32_bf16 v[16:19], v[196:199], v[172:175], v[16:19]
	v_mfma_f32_16x16x32_bf16 v[4:7], v[188:191], v[180:183], v[4:7]
	v_mfma_f32_16x16x32_bf16 v[0:3], v[196:199], v[180:183], v[0:3]
	v_mfma_f32_16x16x32_bf16 v[52:55], v[192:195], v[160:163], v[52:55]
	v_mfma_f32_16x16x32_bf16 v[48:51], v[200:203], v[160:163], v[48:51]
	v_mfma_f32_16x16x32_bf16 v[36:39], v[192:195], v[168:171], v[36:39]
	v_mfma_f32_16x16x32_bf16 v[32:35], v[200:203], v[168:171], v[32:35]
	v_mfma_f32_16x16x32_bf16 v[20:23], v[192:195], v[176:179], v[20:23]
	v_mfma_f32_16x16x32_bf16 v[16:19], v[200:203], v[176:179], v[16:19]
	v_mfma_f32_16x16x32_bf16 v[4:7], v[192:195], v[184:187], v[4:7]
	s_setprio 0
	v_mfma_f32_16x16x32_bf16 v[0:3], v[200:203], v[184:187], v[0:3]
	s_barrier
	ds_read_b128 v[136:139], v148
	ds_read_b128 v[140:143], v148 offset:1024
	ds_read_b128 v[144:147], v148 offset:2048
	ds_read_b128 v[148:151], v148 offset:3072
	s_add_u32 s28, s28, 0x80000
	s_addc_u32 s29, s29, 0
	s_mov_b32 m0, s39
	v_lshl_add_u64 v[188:189], s[28:29], 0, v[128:129]
	ds_read_b128 v[156:159], v135 offset:32768
	ds_read_b128 v[160:163], v135 offset:33792
	ds_read_b128 v[164:167], v135 offset:34816
	ds_read_b128 v[168:171], v135 offset:35840
	ds_read_b128 v[172:175], v135 offset:36864
	ds_read_b128 v[176:179], v135 offset:37888
	ds_read_b128 v[180:183], v135 offset:38912
	ds_read_b128 v[184:187], v135 offset:39936
	global_load_lds_dwordx4 v[188:189], off
	s_mov_b32 m0, s40
	v_lshl_add_u64 v[188:189], s[28:29], 0, v[130:131]
	global_load_lds_dwordx4 v[188:189], off
	s_waitcnt lgkmcnt(8)
	s_barrier
	s_waitcnt lgkmcnt(7)
	v_mfma_f32_16x16x32_bf16 v[124:127], v[136:139], v[156:159], v[124:127]
	s_setprio 1
	v_mfma_f32_16x16x32_bf16 v[120:123], v[144:147], v[156:159], v[120:123]
	s_waitcnt lgkmcnt(5)
	v_mfma_f32_16x16x32_bf16 v[108:111], v[136:139], v[164:167], v[108:111]
	v_mfma_f32_16x16x32_bf16 v[104:107], v[144:147], v[164:167], v[104:107]
	s_waitcnt lgkmcnt(3)
	v_mfma_f32_16x16x32_bf16 v[92:95], v[136:139], v[172:175], v[92:95]
	v_mfma_f32_16x16x32_bf16 v[88:91], v[144:147], v[172:175], v[88:91]
	s_waitcnt lgkmcnt(1)
	v_mfma_f32_16x16x32_bf16 v[76:79], v[136:139], v[180:183], v[76:79]
	v_mfma_f32_16x16x32_bf16 v[72:75], v[144:147], v[180:183], v[72:75]
	v_mfma_f32_16x16x32_bf16 v[124:127], v[140:143], v[160:163], v[124:127]
	v_mfma_f32_16x16x32_bf16 v[120:123], v[148:151], v[160:163], v[120:123]
	v_mfma_f32_16x16x32_bf16 v[108:111], v[140:143], v[168:171], v[108:111]
	v_mfma_f32_16x16x32_bf16 v[104:107], v[148:151], v[168:171], v[104:107]
	v_mfma_f32_16x16x32_bf16 v[92:95], v[140:143], v[176:179], v[92:95]
	v_mfma_f32_16x16x32_bf16 v[88:91], v[148:151], v[176:179], v[88:91]
	s_waitcnt lgkmcnt(0)
	v_mfma_f32_16x16x32_bf16 v[76:79], v[140:143], v[184:187], v[76:79]
	s_setprio 0
	v_mfma_f32_16x16x32_bf16 v[72:75], v[148:151], v[184:187], v[72:75]
	s_barrier
	s_add_i32 s56, 0, 0x1c000
	s_add_u32 s28, s24, 0x4000
	s_addc_u32 s29, s25, 0
	s_add_i32 s55, s55, s36
	v_add_u32_e32 v152, s56, v134
	v_lshl_add_u64 v[204:205], s[28:29], 0, v[128:129]
	s_mov_b32 m0, s55
	ds_read_b128 v[188:191], v152
	ds_read_b128 v[192:195], v152 offset:1024
	ds_read_b128 v[196:199], v152 offset:2048
	ds_read_b128 v[200:203], v152 offset:3072
	global_load_lds_dwordx4 v[204:205], off
	s_add_i32 m0, s55, 0x2000
	v_lshl_add_u64 v[204:205], s[28:29], 0, v[130:131]
	global_load_lds_dwordx4 v[204:205], off
	s_barrier
; #define PG8_STAGE(bufoff, gbase, voff) do { _Pragma("unroll") for (int _i = 0; _i < 2; ++_i) \
;         __builtin_amdgcn_global_load_lds((const unsigned*)((const char*)(gbase) + (voff)[_i]), (LAS unsigned*)(lds + (bufoff) + ldsw + _i * 8192), 16, 0, 0); } while (0)
; #define PG8_LDA(dst, b, h) do { _Pragma("unroll") for (int m = 0; m < 4; ++m) _Pragma("unroll") for (int k = 0; k < 2; ++k) dst[m][k] = *(const LAS bf16x8*)(lds + PG8_SA(b, h) + aoff + m * 2048 + k * 1024); } while (0)
; #define PG8_LDB(dst, b, h) do { _Pragma("unroll") for (int n = 0; n < 2; ++n) _Pragma("unroll") for (int k = 0; k < 2; ++k) dst[n][k] = *(const LAS bf16x8*)(lds + PG8_SB(b, h) + boff + n * 2048 + k * 1024); } while (0)
; #define PG8_MMA(ai, bj, At, Bt) do { __builtin_amdgcn_s_setprio(1); _Pragma("unroll") for (int m = 0; m < 4; ++m) _Pragma("unroll") for (int n = 0; n < 2; ++n) _Pragma("unroll") for (int k = 0; k < 2; ++k) \
;         acc[ai][bj][m][n] = __builtin_amdgcn_mfma_f32_16x16x32_bf16(Bt[n][k], At[m][k], acc[ai][bj][m][n], 0, 0, 0); __builtin_amdgcn_s_setprio(0); } while (0)
; #define PG8_WAIT_V(n) asm volatile("s_waitcnt vmcnt(" #n ")" ::: "memory")
; #define PG8_WAIT_L(n) asm volatile("s_waitcnt lgkmcnt(" #n ")" ::: "memory")
; #define PG8_BAR __builtin_amdgcn_s_barrier()
; #define PG8_SCHED __builtin_amdgcn_sched_barrier(0)
; template <class Epi>
; __device__ __forceinline__ void gemm_phase(LAS unsigned char* lds, const Gemm g, const StaticOrder& S, const Epi& E) {
;     ...
;             PG8_WAIT_L(8); PG8_BAR; PG8_WAIT_L(0); PG8_MMA(0, 0, At, B0); PG8_BAR; PG8_SCHED;
;             PG8_LDB(B1, 1, 1); PG8_STAGE(PG8_SB(1, 0), b3, voffB);
;             PG8_BAR; PG8_WAIT_L(0); PG8_MMA(0, 1, At, B1); PG8_BAR;
;             PG8_LDA(At, 1, 1); PG8_STAGE(PG8_SA(1, 0), a3, voffA);
;             PG8_BAR; PG8_WAIT_L(0); PG8_MMA(1, 0, At, B0); PG8_BAR; PG8_SCHED;
;             PG8_STAGE(PG8_SB(1, 1), b3 + hstepB, voffB);
;             PG8_WAIT_V(6); PG8_BAR; PG8_MMA(1, 1, At, B1); PG8_BAR;
	s_waitcnt lgkmcnt(3)
	v_mfma_f32_16x16x32_bf16 v[116:119], v[188:191], v[156:159], v[116:119]
	s_setprio 1
	s_waitcnt lgkmcnt(1)
	v_mfma_f32_16x16x32_bf16 v[112:115], v[196:199], v[156:159], v[112:115]
	s_mov_b32 m0, s43
	v_lshl_add_u64 v[204:205], s[26:27], 0, v[128:129]
	v_mfma_f32_16x16x32_bf16 v[100:103], v[188:191], v[164:167], v[100:103]
	v_mfma_f32_16x16x32_bf16 v[96:99], v[196:199], v[164:167], v[96:99]
	v_mfma_f32_16x16x32_bf16 v[84:87], v[188:191], v[172:175], v[84:87]
	v_mfma_f32_16x16x32_bf16 v[80:83], v[196:199], v[172:175], v[80:83]
	v_mfma_f32_16x16x32_bf16 v[68:71], v[188:191], v[180:183], v[68:71]
	v_mfma_f32_16x16x32_bf16 v[64:67], v[196:199], v[180:183], v[64:67]
	v_mfma_f32_16x16x32_bf16 v[116:119], v[192:195], v[160:163], v[116:119]
	s_waitcnt lgkmcnt(0)
	v_mfma_f32_16x16x32_bf16 v[112:115], v[200:203], v[160:163], v[112:115]
	v_mfma_f32_16x16x32_bf16 v[100:103], v[192:195], v[168:171], v[100:103]
	v_mfma_f32_16x16x32_bf16 v[96:99], v[200:203], v[168:171], v[96:99]
	v_mfma_f32_16x16x32_bf16 v[84:87], v[192:195], v[176:179], v[84:87]
	v_mfma_f32_16x16x32_bf16 v[80:83], v[200:203], v[176:179], v[80:83]
	v_mfma_f32_16x16x32_bf16 v[68:71], v[192:195], v[184:187], v[68:71]
	s_setprio 0
	v_mfma_f32_16x16x32_bf16 v[64:67], v[200:203], v[184:187], v[64:67]
	s_barrier
	ds_read_b128 v[156:159], v135 offset:49152
	ds_read_b128 v[160:163], v135 offset:50176
	ds_read_b128 v[164:167], v135 offset:51200
	ds_read_b128 v[168:171], v135 offset:52224
	ds_read_b128 v[172:175], v135 offset:53248
	ds_read_b128 v[176:179], v135 offset:54272
	ds_read_b128 v[180:183], v135 offset:55296
	ds_read_b128 v[184:187], v135 offset:56320
	global_load_lds_dwordx4 v[204:205], off
	s_mov_b32 m0, s44
	v_lshl_add_u64 v[204:205], s[26:27], 0, v[130:131]
	global_load_lds_dwordx4 v[204:205], off
	s_barrier
	s_waitcnt lgkmcnt(7)
	v_mfma_f32_16x16x32_bf16 v[60:63], v[136:139], v[156:159], v[60:63]
	s_setprio 1
	v_mfma_f32_16x16x32_bf16 v[56:59], v[144:147], v[156:159], v[56:59]
	s_waitcnt lgkmcnt(5)
	v_mfma_f32_16x16x32_bf16 v[44:47], v[136:139], v[164:167], v[44:47]
	v_mfma_f32_16x16x32_bf16 v[40:43], v[144:147], v[164:167], v[40:43]
	s_waitcnt lgkmcnt(3)
	v_mfma_f32_16x16x32_bf16 v[28:31], v[136:139], v[172:175], v[28:31]
	v_mfma_f32_16x16x32_bf16 v[24:27], v[144:147], v[172:175], v[24:27]
	s_waitcnt lgkmcnt(1)
	v_mfma_f32_16x16x32_bf16 v[12:15], v[136:139], v[180:183], v[12:15]
	v_mfma_f32_16x16x32_bf16 v[8:11], v[144:147], v[180:183], v[8:11]
	v_mfma_f32_16x16x32_bf16 v[60:63], v[140:143], v[160:163], v[60:63]
	v_mfma_f32_16x16x32_bf16 v[56:59], v[148:151], v[160:163], v[56:59]
	v_mfma_f32_16x16x32_bf16 v[44:47], v[140:143], v[168:171], v[44:47]
	v_mfma_f32_16x16x32_bf16 v[40:43], v[148:151], v[168:171], v[40:43]
	v_mfma_f32_16x16x32_bf16 v[28:31], v[140:143], v[176:179], v[28:31]
	v_mfma_f32_16x16x32_bf16 v[24:27], v[148:151], v[176:179], v[24:27]
	s_waitcnt lgkmcnt(0)
	v_mfma_f32_16x16x32_bf16 v[12:15], v[140:143], v[184:187], v[12:15]
	s_setprio 0
	v_mfma_f32_16x16x32_bf16 v[8:11], v[148:151], v[184:187], v[8:11]
	s_barrier
	s_add_u32 s24, s24, 0x84000
	s_addc_u32 s25, s25, 0
	s_add_i32 s26, s56, s36
	s_mov_b32 m0, s26
	v_lshl_add_u64 v[136:137], s[24:25], 0, v[128:129]
	global_load_lds_dwordx4 v[136:137], off
	s_add_i32 m0, s26, 0x2000
	v_lshl_add_u64 v[136:137], s[24:25], 0, v[130:131]
	global_load_lds_dwordx4 v[136:137], off
	s_waitcnt vmcnt(6)
	s_barrier
	v_mfma_f32_16x16x32_bf16 v[52:55], v[188:191], v[156:159], v[52:55]
	s_setprio 1
	v_mfma_f32_16x16x32_bf16 v[48:51], v[196:199], v[156:159], v[48:51]
	s_add_i32 s54, s54, 2
	s_add_u32 s22, s22, 0x8000
	s_addc_u32 s23, s23, 0
	s_add_u32 s51, s51, 0x8000
	s_addc_u32 s52, s52, 0
	v_mfma_f32_16x16x32_bf16 v[36:39], v[188:191], v[164:167], v[36:39]
	v_mfma_f32_16x16x32_bf16 v[32:35], v[196:199], v[164:167], v[32:35]
	v_mfma_f32_16x16x32_bf16 v[20:23], v[188:191], v[172:175], v[20:23]
	v_mfma_f32_16x16x32_bf16 v[16:19], v[196:199], v[172:175], v[16:19]
	v_mfma_f32_16x16x32_bf16 v[4:7], v[188:191], v[180:183], v[4:7]
	v_mfma_f32_16x16x32_bf16 v[0:3], v[196:199], v[180:183], v[0:3]
	v_mfma_f32_16x16x32_bf16 v[52:55], v[192:195], v[160:163], v[52:55]
	v_mfma_f32_16x16x32_bf16 v[48:51], v[200:203], v[160:163], v[48:51]
	v_mfma_f32_16x16x32_bf16 v[36:39], v[192:195], v[168:171], v[36:39]
	v_mfma_f32_16x16x32_bf16 v[32:35], v[200:203], v[168:171], v[32:35]
	v_mfma_f32_16x16x32_bf16 v[20:23], v[192:195], v[176:179], v[20:23]
	v_mfma_f32_16x16x32_bf16 v[16:19], v[200:203], v[176:179], v[16:19]
	v_mfma_f32_16x16x32_bf16 v[4:7], v[192:195], v[184:187], v[4:7]
	s_cmp_gt_u32 s54, 29
	s_setprio 0
	v_mfma_f32_16x16x32_bf16 v[0:3], v[200:203], v[184:187], v[0:3]
	s_barrier
	s_cbranch_scc0 .LBB0_141

; #define PG8_STAGE(bufoff, gbase, voff) do { _Pragma("unroll") for (int _i = 0; _i < 2; ++_i) \
;         __builtin_amdgcn_global_load_lds((const unsigned*)((const char*)(gbase) + (voff)[_i]), (LAS unsigned*)(lds + (bufoff) + ldsw + _i * 8192), 16, 0, 0); } while (0)
; #define PG8_LDA(dst, b, h) do { _Pragma("unroll") for (int m = 0; m < 4; ++m) _Pragma("unroll") for (int k = 0; k < 2; ++k) dst[m][k] = *(const LAS bf16x8*)(lds + PG8_SA(b, h) + aoff + m * 2048 + k * 1024); } while (0)
; #define PG8_LDB(dst, b, h) do { _Pragma("unroll") for (int n = 0; n < 2; ++n) _Pragma("unroll") for (int k = 0; k < 2; ++k) dst[n][k] = *(const LAS bf16x8*)(lds + PG8_SB(b, h) + boff + n * 2048 + k * 1024); } while (0)
; #define PG8_WAIT_V(n) asm volatile("s_waitcnt vmcnt(" #n ")" ::: "memory")
; #define PG8_WAIT_L(n) asm volatile("s_waitcnt lgkmcnt(" #n ")" ::: "memory")
; #define PG8_BAR __builtin_amdgcn_s_barrier()
; template <class Epi>
; __device__ __forceinline__ void gemm_phase(LAS unsigned char* lds, const Gemm g, const StaticOrder& S, const Epi& E) {
;     ...
;         for (int t = 0; t < nt; t += 2) {
;             const bool last = (t == nt - 2);
;             const char* a1 = cA + (size_t)(t + 1) * kstep;
;             const char* a2 = last ? nA : cA + (size_t)(t + 2) * kstep; const char* b2 = last ? nB : cB + (size_t)(t + 2) * kstep;
;             const char* a3 = a2 + kstep; const char* b3 = b2 + kstep;
;             PG8_LDB(B0, 0, 0); PG8_SCHED; PG8_LDA(At, 0, 0); PG8_STAGE(PG8_SA(1, 1), a1 + hstepA, voffA);
;             PG8_WAIT_L(8); PG8_BAR; PG8_WAIT_L(0); PG8_MMA(0, 0, At, B0); PG8_BAR; PG8_SCHED;
;             PG8_LDB(B1, 0, 1); PG8_STAGE(PG8_SB(0, 0), b2, voffB);
;             PG8_BAR; PG8_WAIT_L(0); PG8_MMA(0, 1, At, B1); PG8_BAR;
;             PG8_LDA(At, 0, 1); PG8_STAGE(PG8_SA(0, 0), a2, voffA);
;             PG8_BAR; PG8_WAIT_L(0); PG8_MMA(1, 0, At, B0); PG8_BAR; PG8_SCHED;
;             PG8_STAGE(PG8_SB(0, 1), b2 + hstepB, voffB);
;             PG8_WAIT_V(6); PG8_BAR; PG8_MMA(1, 1, At, B1); PG8_BAR;
;             PG8_LDB(B0, 1, 0); PG8_SCHED; PG8_LDA(At, 1, 0); PG8_STAGE(PG8_SA(0, 1), a2 + hstepA, voffA);
;             PG8_WAIT_L(8); PG8_BAR; PG8_WAIT_L(0); PG8_MMA(0, 0, At, B0); PG8_BAR; PG8_SCHED;
;             PG8_LDB(B1, 1, 1); PG8_STAGE(PG8_SB(1, 0), b3, voffB);
;             PG8_BAR; PG8_WAIT_L(0); PG8_MMA(0, 1, At, B1); PG8_BAR;
.LBB0_186:
	s_add_u32 s4, s24, 0x4000
	s_addc_u32 s5, s25, 0
	s_add_u32 s50, s22, 0x8000
	s_addc_u32 s51, s23, 0
	s_mov_b32 s22, 0
	s_add_i32 s54, s22, 2
	s_add_u32 s23, s4, 0x4000
	s_addc_u32 s24, s5, 0
	s_cmp_eq_u32 s40, s22
	s_cselect_b32 s26, s6, s23
	s_cselect_b32 s27, s7, s24
	s_cselect_b32 s24, s20, s50
	s_cselect_b32 s25, s21, s51
	s_add_u32 s22, s26, 0x4000
	s_addc_u32 s23, s27, 0
	s_add_i32 s55, 0, 0x10000
	v_add_u32_e32 v140, s55, v207
	ds_read_b128 v[128:131], v140
	ds_read_b128 v[132:135], v140 offset:1024
	ds_read_b128 v[136:139], v140 offset:2048
	ds_read_b128 v[140:143], v140 offset:3072
	v_lshl_add_u64 v[186:187], s[4:5], 0, v[158:159]
	s_add_i32 m0, s33, 0xc000
	ds_read_b128 v[144:147], v209
	ds_read_b128 v[148:151], v209 offset:1024
	ds_read_b128 v[162:165], v209 offset:2048
	ds_read_b128 v[166:169], v209 offset:3072
	ds_read_b128 v[170:173], v209 offset:4096
	ds_read_b128 v[174:177], v209 offset:5120
	ds_read_b128 v[178:181], v209 offset:6144
	ds_read_b128 v[182:185], v209 offset:7168
	global_load_lds_dwordx4 v[186:187], off
	s_add_i32 m0, s33, 0xe000
	v_lshl_add_u64 v[186:187], s[4:5], 0, v[160:161]
	global_load_lds_dwordx4 v[186:187], off
	s_waitcnt lgkmcnt(8)
	s_barrier
	s_waitcnt lgkmcnt(7)
	v_mfma_f32_16x16x32_bf16 v[124:127], v[128:131], v[144:147], 0
	s_setprio 1
	v_mfma_f32_16x16x32_bf16 v[120:123], v[136:139], v[144:147], 0
	s_waitcnt lgkmcnt(5)
	v_mfma_f32_16x16x32_bf16 v[116:119], v[128:131], v[162:165], 0
	v_mfma_f32_16x16x32_bf16 v[112:115], v[136:139], v[162:165], 0
	s_waitcnt lgkmcnt(3)
	v_mfma_f32_16x16x32_bf16 v[108:111], v[128:131], v[170:173], 0
	v_mfma_f32_16x16x32_bf16 v[104:107], v[136:139], v[170:173], 0
	s_waitcnt lgkmcnt(1)
	v_mfma_f32_16x16x32_bf16 v[100:103], v[128:131], v[178:181], 0
	v_mfma_f32_16x16x32_bf16 v[96:99], v[136:139], v[178:181], 0
	v_mfma_f32_16x16x32_bf16 v[124:127], v[132:135], v[148:151], v[124:127]
	v_mfma_f32_16x16x32_bf16 v[120:123], v[140:143], v[148:151], v[120:123]
	v_mfma_f32_16x16x32_bf16 v[116:119], v[132:135], v[166:169], v[116:119]
	v_mfma_f32_16x16x32_bf16 v[112:115], v[140:143], v[166:169], v[112:115]
	v_mfma_f32_16x16x32_bf16 v[108:111], v[132:135], v[174:177], v[108:111]
	v_mfma_f32_16x16x32_bf16 v[104:107], v[140:143], v[174:177], v[104:107]
	s_waitcnt lgkmcnt(0)
	v_mfma_f32_16x16x32_bf16 v[100:103], v[132:135], v[182:185], v[100:103]
	s_setprio 0
	v_mfma_f32_16x16x32_bf16 v[96:99], v[140:143], v[182:185], v[96:99]
	s_barrier
	s_add_i32 s58, 0, 0x14000
	s_add_i32 s55, s55, s31
	v_add_u32_e32 v198, s58, v207
	v_lshl_add_u64 v[202:203], s[24:25], 0, v[152:153]
	s_mov_b32 m0, s55
	ds_read_b128 v[186:189], v198
	ds_read_b128 v[190:193], v198 offset:1024
	ds_read_b128 v[194:197], v198 offset:2048
	ds_read_b128 v[198:201], v198 offset:3072
	global_load_lds_dwordx4 v[202:203], off
	s_add_i32 m0, s55, 0x2000
	v_lshl_add_u64 v[202:203], s[24:25], 0, v[156:157]
	global_load_lds_dwordx4 v[202:203], off
	s_barrier
	s_waitcnt lgkmcnt(3)
	v_mfma_f32_16x16x32_bf16 v[92:95], v[186:189], v[144:147], 0
	s_setprio 1
	s_waitcnt lgkmcnt(1)
	v_mfma_f32_16x16x32_bf16 v[88:91], v[194:197], v[144:147], 0
	s_mov_b32 m0, s33
	v_lshl_add_u64 v[202:203], s[26:27], 0, v[152:153]
	v_mfma_f32_16x16x32_bf16 v[84:87], v[186:189], v[162:165], 0
	v_mfma_f32_16x16x32_bf16 v[80:83], v[194:197], v[162:165], 0
	v_mfma_f32_16x16x32_bf16 v[76:79], v[186:189], v[170:173], 0
	v_mfma_f32_16x16x32_bf16 v[72:75], v[194:197], v[170:173], 0
	v_mfma_f32_16x16x32_bf16 v[68:71], v[186:189], v[178:181], 0
	v_mfma_f32_16x16x32_bf16 v[64:67], v[194:197], v[178:181], 0
	v_mfma_f32_16x16x32_bf16 v[92:95], v[190:193], v[148:151], v[92:95]
	s_waitcnt lgkmcnt(0)
	v_mfma_f32_16x16x32_bf16 v[88:91], v[198:201], v[148:151], v[88:91]
	v_mfma_f32_16x16x32_bf16 v[84:87], v[190:193], v[166:169], v[84:87]
	v_mfma_f32_16x16x32_bf16 v[80:83], v[198:201], v[166:169], v[80:83]
	v_mfma_f32_16x16x32_bf16 v[76:79], v[190:193], v[174:177], v[76:79]
	v_mfma_f32_16x16x32_bf16 v[72:75], v[198:201], v[174:177], v[72:75]
	v_mfma_f32_16x16x32_bf16 v[68:71], v[190:193], v[182:185], v[68:71]
	s_setprio 0
	v_mfma_f32_16x16x32_bf16 v[64:67], v[198:201], v[182:185], v[64:67]
	s_barrier
	ds_read_b128 v[144:147], v209 offset:16384
	ds_read_b128 v[148:151], v209 offset:17408
	ds_read_b128 v[162:165], v209 offset:18432
	ds_read_b128 v[166:169], v209 offset:19456
	ds_read_b128 v[170:173], v209 offset:20480
	ds_read_b128 v[174:177], v209 offset:21504
	ds_read_b128 v[178:181], v209 offset:22528
	ds_read_b128 v[182:185], v209 offset:23552
	global_load_lds_dwordx4 v[202:203], off
	s_mov_b32 m0, s34
	v_lshl_add_u64 v[202:203], s[26:27], 0, v[156:157]
	global_load_lds_dwordx4 v[202:203], off
	s_barrier
	s_waitcnt lgkmcnt(7)
	v_mfma_f32_16x16x32_bf16 v[60:63], v[128:131], v[144:147], 0
	s_setprio 1
	v_mfma_f32_16x16x32_bf16 v[56:59], v[136:139], v[144:147], 0
	s_waitcnt lgkmcnt(5)
	v_mfma_f32_16x16x32_bf16 v[52:55], v[128:131], v[162:165], 0
	v_mfma_f32_16x16x32_bf16 v[48:51], v[136:139], v[162:165], 0
	s_waitcnt lgkmcnt(3)
	v_mfma_f32_16x16x32_bf16 v[44:47], v[128:131], v[170:173], 0
	v_mfma_f32_16x16x32_bf16 v[40:43], v[136:139], v[170:173], 0
	s_waitcnt lgkmcnt(1)
	v_mfma_f32_16x16x32_bf16 v[36:39], v[128:131], v[178:181], 0
	v_mfma_f32_16x16x32_bf16 v[32:35], v[136:139], v[178:181], 0
	v_mfma_f32_16x16x32_bf16 v[60:63], v[132:135], v[148:151], v[60:63]
	v_mfma_f32_16x16x32_bf16 v[56:59], v[140:143], v[148:151], v[56:59]
	v_mfma_f32_16x16x32_bf16 v[52:55], v[132:135], v[166:169], v[52:55]
	v_mfma_f32_16x16x32_bf16 v[48:51], v[140:143], v[166:169], v[48:51]
	v_mfma_f32_16x16x32_bf16 v[44:47], v[132:135], v[174:177], v[44:47]
	v_mfma_f32_16x16x32_bf16 v[40:43], v[140:143], v[174:177], v[40:43]
	s_waitcnt lgkmcnt(0)
	v_mfma_f32_16x16x32_bf16 v[36:39], v[132:135], v[182:185], v[36:39]
	s_setprio 0
	v_mfma_f32_16x16x32_bf16 v[32:35], v[140:143], v[182:185], v[32:35]
	s_barrier
; #define PG8_STAGE(bufoff, gbase, voff) do { _Pragma("unroll") for (int _i = 0; _i < 2; ++_i) \
;         __builtin_amdgcn_global_load_lds((const unsigned*)((const char*)(gbase) + (voff)[_i]), (LAS unsigned*)(lds + (bufoff) + ldsw + _i * 8192), 16, 0, 0); } while (0)
; #define PG8_LDA(dst, b, h) do { _Pragma("unroll") for (int m = 0; m < 4; ++m) _Pragma("unroll") for (int k = 0; k < 2; ++k) dst[m][k] = *(const LAS bf16x8*)(lds + PG8_SA(b, h) + aoff + m * 2048 + k * 1024); } while (0)
; #define PG8_LDB(dst, b, h) do { _Pragma("unroll") for (int n = 0; n < 2; ++n) _Pragma("unroll") for (int k = 0; k < 2; ++k) dst[n][k] = *(const LAS bf16x8*)(lds + PG8_SB(b, h) + boff + n * 2048 + k * 1024); } while (0)
; #define PG8_MMA(ai, bj, At, Bt) do { __builtin_amdgcn_s_setprio(1); _Pragma("unroll") for (int m = 0; m < 4; ++m) _Pragma("unroll") for (int n = 0; n < 2; ++n) _Pragma("unroll") for (int k = 0; k < 2; ++k) \
;         acc[ai][bj][m][n] = __builtin_amdgcn_mfma_f32_16x16x32_bf16(Bt[n][k], At[m][k], acc[ai][bj][m][n], 0, 0, 0); __builtin_amdgcn_s_setprio(0); } while (0)
; #define PG8_WAIT_V(n) asm volatile("s_waitcnt vmcnt(" #n ")" ::: "memory")
; #define PG8_WAIT_L(n) asm volatile("s_waitcnt lgkmcnt(" #n ")" ::: "memory")
; #define PG8_BAR __builtin_amdgcn_s_barrier()
; #define PG8_SCHED __builtin_amdgcn_sched_barrier(0)
; template <class Epi>
; __device__ __forceinline__ void gemm_phase(LAS unsigned char* lds, const Gemm g, const StaticOrder& S, const Epi& E) {
;     ...
;             PG8_WAIT_V(6); PG8_BAR; PG8_MMA(1, 1, At, B1); PG8_BAR;
;             PG8_LDB(B0, 1, 0); PG8_SCHED; PG8_LDA(At, 1, 0); PG8_STAGE(PG8_SA(0, 1), a2 + hstepA, voffA);
;             PG8_WAIT_L(8); PG8_BAR; PG8_WAIT_L(0); PG8_MMA(0, 0, At, B0); PG8_BAR; PG8_SCHED;
;             PG8_LDB(B1, 1, 1); PG8_STAGE(PG8_SB(1, 0), b3, voffB);
;             PG8_BAR; PG8_WAIT_L(0); PG8_MMA(0, 1, At, B1); PG8_BAR;
;             PG8_LDA(At, 1, 1); PG8_STAGE(PG8_SA(1, 0), a3, voffA);
;             PG8_BAR; PG8_WAIT_L(0); PG8_MMA(1, 0, At, B0); PG8_BAR; PG8_SCHED;
	s_add_u32 s56, s24, s52
	s_addc_u32 s57, s25, 0
	s_add_i32 s55, s58, s31
	s_mov_b32 m0, s55
	v_lshl_add_u64 v[128:129], s[56:57], 0, v[152:153]
	global_load_lds_dwordx4 v[128:129], off
	s_add_i32 m0, s55, 0x2000
	v_lshl_add_u64 v[128:129], s[56:57], 0, v[156:157]
	global_load_lds_dwordx4 v[128:129], off
	s_waitcnt vmcnt(6)
	s_barrier
	v_mfma_f32_16x16x32_bf16 v[28:31], v[186:189], v[144:147], 0
	s_setprio 1
	v_mfma_f32_16x16x32_bf16 v[24:27], v[194:197], v[144:147], 0
	s_add_i32 s55, 0, 0x18000
	v_add_u32_e32 v140, s55, v207
	v_mfma_f32_16x16x32_bf16 v[20:23], v[186:189], v[162:165], 0
	v_mfma_f32_16x16x32_bf16 v[16:19], v[194:197], v[162:165], 0
	v_mfma_f32_16x16x32_bf16 v[12:15], v[186:189], v[170:173], 0
	v_mfma_f32_16x16x32_bf16 v[8:11], v[194:197], v[170:173], 0
	v_mfma_f32_16x16x32_bf16 v[4:7], v[186:189], v[178:181], 0
	v_mfma_f32_16x16x32_bf16 v[0:3], v[194:197], v[178:181], 0
	v_mfma_f32_16x16x32_bf16 v[28:31], v[190:193], v[148:151], v[28:31]
	v_mfma_f32_16x16x32_bf16 v[24:27], v[198:201], v[148:151], v[24:27]
	v_mfma_f32_16x16x32_bf16 v[20:23], v[190:193], v[166:169], v[20:23]
	v_mfma_f32_16x16x32_bf16 v[16:19], v[198:201], v[166:169], v[16:19]
	v_mfma_f32_16x16x32_bf16 v[12:15], v[190:193], v[174:177], v[12:15]
	v_mfma_f32_16x16x32_bf16 v[8:11], v[198:201], v[174:177], v[8:11]
	v_mfma_f32_16x16x32_bf16 v[4:7], v[190:193], v[182:185], v[4:7]
	s_setprio 0
	v_mfma_f32_16x16x32_bf16 v[0:3], v[198:201], v[182:185], v[0:3]
	s_barrier
	ds_read_b128 v[128:131], v140
	ds_read_b128 v[132:135], v140 offset:1024
	ds_read_b128 v[136:139], v140 offset:2048
	ds_read_b128 v[140:143], v140 offset:3072
	s_add_u32 s26, s26, s52
	s_addc_u32 s27, s27, 0
	s_mov_b32 m0, s35
	v_lshl_add_u64 v[186:187], s[26:27], 0, v[152:153]
	ds_read_b128 v[144:147], v209 offset:32768
	ds_read_b128 v[148:151], v209 offset:33792
	ds_read_b128 v[162:165], v209 offset:34816
	ds_read_b128 v[166:169], v209 offset:35840
	ds_read_b128 v[170:173], v209 offset:36864
	ds_read_b128 v[174:177], v209 offset:37888
	ds_read_b128 v[178:181], v209 offset:38912
	ds_read_b128 v[182:185], v209 offset:39936
	global_load_lds_dwordx4 v[186:187], off
	s_mov_b32 m0, s36
	v_lshl_add_u64 v[186:187], s[26:27], 0, v[156:157]
	global_load_lds_dwordx4 v[186:187], off
	s_waitcnt lgkmcnt(8)
	s_barrier
	s_waitcnt lgkmcnt(7)
	v_mfma_f32_16x16x32_bf16 v[124:127], v[128:131], v[144:147], v[124:127]
	s_setprio 1
	v_mfma_f32_16x16x32_bf16 v[120:123], v[136:139], v[144:147], v[120:123]
	s_waitcnt lgkmcnt(5)
	v_mfma_f32_16x16x32_bf16 v[116:119], v[128:131], v[162:165], v[116:119]
	v_mfma_f32_16x16x32_bf16 v[112:115], v[136:139], v[162:165], v[112:115]
	s_waitcnt lgkmcnt(3)
	v_mfma_f32_16x16x32_bf16 v[108:111], v[128:131], v[170:173], v[108:111]
	v_mfma_f32_16x16x32_bf16 v[104:107], v[136:139], v[170:173], v[104:107]
	s_waitcnt lgkmcnt(1)
	v_mfma_f32_16x16x32_bf16 v[100:103], v[128:131], v[178:181], v[100:103]
	v_mfma_f32_16x16x32_bf16 v[96:99], v[136:139], v[178:181], v[96:99]
	v_mfma_f32_16x16x32_bf16 v[124:127], v[132:135], v[148:151], v[124:127]
	v_mfma_f32_16x16x32_bf16 v[120:123], v[140:143], v[148:151], v[120:123]
	v_mfma_f32_16x16x32_bf16 v[116:119], v[132:135], v[166:169], v[116:119]
	v_mfma_f32_16x16x32_bf16 v[112:115], v[140:143], v[166:169], v[112:115]
	v_mfma_f32_16x16x32_bf16 v[108:111], v[132:135], v[174:177], v[108:111]
	v_mfma_f32_16x16x32_bf16 v[104:107], v[140:143], v[174:177], v[104:107]
	s_waitcnt lgkmcnt(0)
	v_mfma_f32_16x16x32_bf16 v[100:103], v[132:135], v[182:185], v[100:103]
	s_setprio 0
	v_mfma_f32_16x16x32_bf16 v[96:99], v[140:143], v[182:185], v[96:99]
	s_barrier
	s_add_i32 s26, 0, 0x1c000
	s_add_u32 s24, s24, 0x4000
	s_addc_u32 s25, s25, 0
	s_add_i32 s27, s55, s31
	v_add_u32_e32 v198, s26, v207
	v_lshl_add_u64 v[202:203], s[24:25], 0, v[152:153]
	s_mov_b32 m0, s27
	ds_read_b128 v[186:189], v198
	ds_read_b128 v[190:193], v198 offset:1024
	ds_read_b128 v[194:197], v198 offset:2048
	ds_read_b128 v[198:201], v198 offset:3072
	global_load_lds_dwordx4 v[202:203], off
	s_add_i32 m0, s27, 0x2000
	v_lshl_add_u64 v[202:203], s[24:25], 0, v[156:157]
	global_load_lds_dwordx4 v[202:203], off
	s_barrier
	s_waitcnt lgkmcnt(3)
	v_mfma_f32_16x16x32_bf16 v[92:95], v[186:189], v[144:147], v[92:95]
	s_setprio 1
	s_waitcnt lgkmcnt(1)
	v_mfma_f32_16x16x32_bf16 v[88:91], v[194:197], v[144:147], v[88:91]
	s_mov_b32 m0, s38
	v_lshl_add_u64 v[202:203], s[22:23], 0, v[152:153]
	v_mfma_f32_16x16x32_bf16 v[84:87], v[186:189], v[162:165], v[84:87]
	v_mfma_f32_16x16x32_bf16 v[80:83], v[194:197], v[162:165], v[80:83]
	v_mfma_f32_16x16x32_bf16 v[76:79], v[186:189], v[170:173], v[76:79]
	v_mfma_f32_16x16x32_bf16 v[72:75], v[194:197], v[170:173], v[72:75]
	v_mfma_f32_16x16x32_bf16 v[68:71], v[186:189], v[178:181], v[68:71]
	v_mfma_f32_16x16x32_bf16 v[64:67], v[194:197], v[178:181], v[64:67]
	v_mfma_f32_16x16x32_bf16 v[92:95], v[190:193], v[148:151], v[92:95]
	s_waitcnt lgkmcnt(0)
	v_mfma_f32_16x16x32_bf16 v[88:91], v[198:201], v[148:151], v[88:91]
	v_mfma_f32_16x16x32_bf16 v[84:87], v[190:193], v[166:169], v[84:87]
	v_mfma_f32_16x16x32_bf16 v[80:83], v[198:201], v[166:169], v[80:83]
	v_mfma_f32_16x16x32_bf16 v[76:79], v[190:193], v[174:177], v[76:79]
	v_mfma_f32_16x16x32_bf16 v[72:75], v[198:201], v[174:177], v[72:75]
	v_mfma_f32_16x16x32_bf16 v[68:71], v[190:193], v[182:185], v[68:71]
	s_setprio 0
	v_mfma_f32_16x16x32_bf16 v[64:67], v[198:201], v[182:185], v[64:67]
	s_barrier
; #define PG8_STAGE(bufoff, gbase, voff) do { _Pragma("unroll") for (int _i = 0; _i < 2; ++_i) \
;         __builtin_amdgcn_global_load_lds((const unsigned*)((const char*)(gbase) + (voff)[_i]), (LAS unsigned*)(lds + (bufoff) + ldsw + _i * 8192), 16, 0, 0); } while (0)
; #define PG8_LDA(dst, b, h) do { _Pragma("unroll") for (int m = 0; m < 4; ++m) _Pragma("unroll") for (int k = 0; k < 2; ++k) dst[m][k] = *(const LAS bf16x8*)(lds + PG8_SA(b, h) + aoff + m * 2048 + k * 1024); } while (0)
; #define PG8_LDB(dst, b, h) do { _Pragma("unroll") for (int n = 0; n < 2; ++n) _Pragma("unroll") for (int k = 0; k < 2; ++k) dst[n][k] = *(const LAS bf16x8*)(lds + PG8_SB(b, h) + boff + n * 2048 + k * 1024); } while (0)
; #define PG8_MMA(ai, bj, At, Bt) do { __builtin_amdgcn_s_setprio(1); _Pragma("unroll") for (int m = 0; m < 4; ++m) _Pragma("unroll") for (int n = 0; n < 2; ++n) _Pragma("unroll") for (int k = 0; k < 2; ++k) \
;         acc[ai][bj][m][n] = __builtin_amdgcn_mfma_f32_16x16x32_bf16(Bt[n][k], At[m][k], acc[ai][bj][m][n], 0, 0, 0); __builtin_amdgcn_s_setprio(0); } while (0)
; #define PG8_WAIT_V(n) asm volatile("s_waitcnt vmcnt(" #n ")" ::: "memory")
; #define PG8_WAIT_L(n) asm volatile("s_waitcnt lgkmcnt(" #n ")" ::: "memory")
; #define PG8_BAR __builtin_amdgcn_s_barrier()
; #define PG8_SCHED __builtin_amdgcn_sched_barrier(0)
; template <class Epi>
; __device__ __forceinline__ void gemm_phase(LAS unsigned char* lds, const Gemm g, const StaticOrder& S, const Epi& E) {
;     ...
;             PG8_WAIT_L(8); PG8_BAR; PG8_WAIT_L(0); PG8_MMA(0, 0, At, B0); PG8_BAR; PG8_SCHED;
;             PG8_LDB(B1, 1, 1); PG8_STAGE(PG8_SB(1, 0), b3, voffB);
;             PG8_BAR; PG8_WAIT_L(0); PG8_MMA(0, 1, At, B1); PG8_BAR;
;             PG8_LDA(At, 1, 1); PG8_STAGE(PG8_SA(1, 0), a3, voffA);
;             PG8_BAR; PG8_WAIT_L(0); PG8_MMA(1, 0, At, B0); PG8_BAR; PG8_SCHED;
;             PG8_STAGE(PG8_SB(1, 1), b3 + hstepB, voffB);
;             PG8_WAIT_V(6); PG8_BAR; PG8_MMA(1, 1, At, B1); PG8_BAR;
	ds_read_b128 v[144:147], v209 offset:49152
	ds_read_b128 v[148:151], v209 offset:50176
	ds_read_b128 v[162:165], v209 offset:51200
	ds_read_b128 v[166:169], v209 offset:52224
	ds_read_b128 v[170:173], v209 offset:53248
	ds_read_b128 v[174:177], v209 offset:54272
	ds_read_b128 v[178:181], v209 offset:55296
	ds_read_b128 v[182:185], v209 offset:56320
	global_load_lds_dwordx4 v[202:203], off
	s_mov_b32 m0, s39
	v_lshl_add_u64 v[202:203], s[22:23], 0, v[156:157]
	global_load_lds_dwordx4 v[202:203], off
	s_barrier
	s_waitcnt lgkmcnt(7)
	v_mfma_f32_16x16x32_bf16 v[60:63], v[128:131], v[144:147], v[60:63]
	s_setprio 1
	v_mfma_f32_16x16x32_bf16 v[56:59], v[136:139], v[144:147], v[56:59]
	s_waitcnt lgkmcnt(5)
	v_mfma_f32_16x16x32_bf16 v[52:55], v[128:131], v[162:165], v[52:55]
	v_mfma_f32_16x16x32_bf16 v[48:51], v[136:139], v[162:165], v[48:51]
	s_waitcnt lgkmcnt(3)
	v_mfma_f32_16x16x32_bf16 v[44:47], v[128:131], v[170:173], v[44:47]
	v_mfma_f32_16x16x32_bf16 v[40:43], v[136:139], v[170:173], v[40:43]
	s_waitcnt lgkmcnt(1)
	v_mfma_f32_16x16x32_bf16 v[36:39], v[128:131], v[178:181], v[36:39]
	v_mfma_f32_16x16x32_bf16 v[32:35], v[136:139], v[178:181], v[32:35]
	v_mfma_f32_16x16x32_bf16 v[60:63], v[132:135], v[148:151], v[60:63]
	v_mfma_f32_16x16x32_bf16 v[56:59], v[140:143], v[148:151], v[56:59]
	v_mfma_f32_16x16x32_bf16 v[52:55], v[132:135], v[166:169], v[52:55]
	v_mfma_f32_16x16x32_bf16 v[48:51], v[140:143], v[166:169], v[48:51]
	v_mfma_f32_16x16x32_bf16 v[44:47], v[132:135], v[174:177], v[44:47]
	v_mfma_f32_16x16x32_bf16 v[40:43], v[140:143], v[174:177], v[40:43]
	s_waitcnt lgkmcnt(0)
	v_mfma_f32_16x16x32_bf16 v[36:39], v[132:135], v[182:185], v[36:39]
	s_setprio 0
	v_mfma_f32_16x16x32_bf16 v[32:35], v[140:143], v[182:185], v[32:35]
	s_barrier
	s_add_u32 s22, s24, s52
	s_addc_u32 s23, s25, 0
	s_add_i32 s24, s26, s31
	s_mov_b32 m0, s24
	v_lshl_add_u64 v[128:129], s[22:23], 0, v[152:153]
	global_load_lds_dwordx4 v[128:129], off
	s_add_i32 m0, s24, 0x2000
	v_lshl_add_u64 v[128:129], s[22:23], 0, v[156:157]
	global_load_lds_dwordx4 v[128:129], off
	s_waitcnt vmcnt(6)
	s_barrier
	v_mfma_f32_16x16x32_bf16 v[28:31], v[186:189], v[144:147], v[28:31]
	s_setprio 1
	v_mfma_f32_16x16x32_bf16 v[24:27], v[194:197], v[144:147], v[24:27]
	s_add_u32 s4, s4, 0x8000
	s_addc_u32 s5, s5, 0
	s_add_u32 s50, s50, 0x8000
	s_addc_u32 s51, s51, 0
	v_mfma_f32_16x16x32_bf16 v[20:23], v[186:189], v[162:165], v[20:23]
	v_mfma_f32_16x16x32_bf16 v[16:19], v[194:197], v[162:165], v[16:19]
	v_mfma_f32_16x16x32_bf16 v[12:15], v[186:189], v[170:173], v[12:15]
	v_mfma_f32_16x16x32_bf16 v[8:11], v[194:197], v[170:173], v[8:11]
	v_mfma_f32_16x16x32_bf16 v[4:7], v[186:189], v[178:181], v[4:7]
	v_mfma_f32_16x16x32_bf16 v[0:3], v[194:197], v[178:181], v[0:3]
	v_mfma_f32_16x16x32_bf16 v[28:31], v[190:193], v[148:151], v[28:31]
	v_mfma_f32_16x16x32_bf16 v[24:27], v[198:201], v[148:151], v[24:27]
	v_mfma_f32_16x16x32_bf16 v[20:23], v[190:193], v[166:169], v[20:23]
	v_mfma_f32_16x16x32_bf16 v[16:19], v[198:201], v[166:169], v[16:19]
	v_mfma_f32_16x16x32_bf16 v[12:15], v[190:193], v[174:177], v[12:15]
	v_mfma_f32_16x16x32_bf16 v[8:11], v[198:201], v[174:177], v[8:11]
	v_mfma_f32_16x16x32_bf16 v[4:7], v[190:193], v[182:185], v[4:7]
	s_cmp_ge_u32 s54, s28
	s_mov_b32 s22, s54
	s_setprio 0
	v_mfma_f32_16x16x32_bf16 v[0:3], v[198:201], v[182:185], v[0:3]
	s_barrier
	s_cbranch_scc0 .LBB0_187
	s_branch .Lpeel_done_187
.LBB0_187:
	s_add_i32 s54, s22, 2
	s_add_u32 s23, s4, 0x4000
	s_addc_u32 s24, s5, 0
	s_cmp_eq_u32 s40, s22
	s_cselect_b32 s26, s6, s23
	s_cselect_b32 s27, s7, s24
	s_cselect_b32 s24, s20, s50
	s_cselect_b32 s25, s21, s51
	s_add_u32 s22, s26, 0x4000
	s_addc_u32 s23, s27, 0
	s_add_i32 s55, 0, 0x10000
	v_add_u32_e32 v140, s55, v207
	ds_read_b128 v[128:131], v140
	ds_read_b128 v[132:135], v140 offset:1024
	ds_read_b128 v[136:139], v140 offset:2048
	ds_read_b128 v[140:143], v140 offset:3072
	v_lshl_add_u64 v[186:187], s[4:5], 0, v[158:159]
	s_add_i32 m0, s33, 0xc000
	ds_read_b128 v[144:147], v209
	ds_read_b128 v[148:151], v209 offset:1024
	ds_read_b128 v[162:165], v209 offset:2048
	ds_read_b128 v[166:169], v209 offset:3072
	ds_read_b128 v[170:173], v209 offset:4096
	ds_read_b128 v[174:177], v209 offset:5120
	ds_read_b128 v[178:181], v209 offset:6144
	ds_read_b128 v[182:185], v209 offset:7168
	global_load_lds_dwordx4 v[186:187], off
	s_add_i32 m0, s33, 0xe000
	v_lshl_add_u64 v[186:187], s[4:5], 0, v[160:161]
	global_load_lds_dwordx4 v[186:187], off
	s_waitcnt lgkmcnt(8)
	s_barrier
	s_waitcnt lgkmcnt(7)
	v_mfma_f32_16x16x32_bf16 v[124:127], v[128:131], v[144:147], v[124:127]
	s_setprio 1
	v_mfma_f32_16x16x32_bf16 v[120:123], v[136:139], v[144:147], v[120:123]
	s_waitcnt lgkmcnt(5)
	v_mfma_f32_16x16x32_bf16 v[116:119], v[128:131], v[162:165], v[116:119]
	v_mfma_f32_16x16x32_bf16 v[112:115], v[136:139], v[162:165], v[112:115]
	s_waitcnt lgkmcnt(3)
	v_mfma_f32_16x16x32_bf16 v[108:111], v[128:131], v[170:173], v[108:111]
	v_mfma_f32_16x16x32_bf16 v[104:107], v[136:139], v[170:173], v[104:107]
	s_waitcnt lgkmcnt(1)
	v_mfma_f32_16x16x32_bf16 v[100:103], v[128:131], v[178:181], v[100:103]
	v_mfma_f32_16x16x32_bf16 v[96:99], v[136:139], v[178:181], v[96:99]
	v_mfma_f32_16x16x32_bf16 v[124:127], v[132:135], v[148:151], v[124:127]
	v_mfma_f32_16x16x32_bf16 v[120:123], v[140:143], v[148:151], v[120:123]
	v_mfma_f32_16x16x32_bf16 v[116:119], v[132:135], v[166:169], v[116:119]
	v_mfma_f32_16x16x32_bf16 v[112:115], v[140:143], v[166:169], v[112:115]
	v_mfma_f32_16x16x32_bf16 v[108:111], v[132:135], v[174:177], v[108:111]
	v_mfma_f32_16x16x32_bf16 v[104:107], v[140:143], v[174:177], v[104:107]
	s_waitcnt lgkmcnt(0)
	v_mfma_f32_16x16x32_bf16 v[100:103], v[132:135], v[182:185], v[100:103]
	s_setprio 0
	v_mfma_f32_16x16x32_bf16 v[96:99], v[140:143], v[182:185], v[96:99]
	s_barrier
; #define PG8_STAGE(bufoff, gbase, voff) do { _Pragma("unroll") for (int _i = 0; _i < 2; ++_i) \
;         __builtin_amdgcn_global_load_lds((const unsigned*)((const char*)(gbase) + (voff)[_i]), (LAS unsigned*)(lds + (bufoff) + ldsw + _i * 8192), 16, 0, 0); } while (0)
; #define PG8_LDA(dst, b, h) do { _Pragma("unroll") for (int m = 0; m < 4; ++m) _Pragma("unroll") for (int k = 0; k < 2; ++k) dst[m][k] = *(const LAS bf16x8*)(lds + PG8_SA(b, h) + aoff + m * 2048 + k * 1024); } while (0)
; #define PG8_LDB(dst, b, h) do { _Pragma("unroll") for (int n = 0; n < 2; ++n) _Pragma("unroll") for (int k = 0; k < 2; ++k) dst[n][k] = *(const LAS bf16x8*)(lds + PG8_SB(b, h) + boff + n * 2048 + k * 1024); } while (0)
; #define PG8_MMA(ai, bj, At, Bt) do { __builtin_amdgcn_s_setprio(1); _Pragma("unroll") for (int m = 0; m < 4; ++m) _Pragma("unroll") for (int n = 0; n < 2; ++n) _Pragma("unroll") for (int k = 0; k < 2; ++k) \
;         acc[ai][bj][m][n] = __builtin_amdgcn_mfma_f32_16x16x32_bf16(Bt[n][k], At[m][k], acc[ai][bj][m][n], 0, 0, 0); __builtin_amdgcn_s_setprio(0); } while (0)
; #define PG8_WAIT_V(n) asm volatile("s_waitcnt vmcnt(" #n ")" ::: "memory")
; #define PG8_WAIT_L(n) asm volatile("s_waitcnt lgkmcnt(" #n ")" ::: "memory")
; #define PG8_BAR __builtin_amdgcn_s_barrier()
; #define PG8_SCHED __builtin_amdgcn_sched_barrier(0)
; template <class Epi>
; __device__ __forceinline__ void gemm_phase(LAS unsigned char* lds, const Gemm g, const StaticOrder& S, const Epi& E) {
;     ...
;             PG8_LDB(B1, 0, 1); PG8_STAGE(PG8_SB(0, 0), b2, voffB);
;             PG8_BAR; PG8_WAIT_L(0); PG8_MMA(0, 1, At, B1); PG8_BAR;
;             PG8_LDA(At, 0, 1); PG8_STAGE(PG8_SA(0, 0), a2, voffA);
;             PG8_BAR; PG8_WAIT_L(0); PG8_MMA(1, 0, At, B0); PG8_BAR; PG8_SCHED;
;             PG8_STAGE(PG8_SB(0, 1), b2 + hstepB, voffB);
;             PG8_WAIT_V(6); PG8_BAR; PG8_MMA(1, 1, At, B1); PG8_BAR;
;             PG8_LDB(B0, 1, 0); PG8_SCHED; PG8_LDA(At, 1, 0); PG8_STAGE(PG8_SA(0, 1), a2 + hstepA, voffA);
;             PG8_WAIT_L(8); PG8_BAR; PG8_WAIT_L(0); PG8_MMA(0, 0, At, B0); PG8_BAR; PG8_SCHED;
;             PG8_LDB(B1, 1, 1); PG8_STAGE(PG8_SB(1, 0), b3, voffB);
;             PG8_BAR; PG8_WAIT_L(0); PG8_MMA(0, 1, At, B1); PG8_BAR;
	s_add_i32 s58, 0, 0x14000
	s_add_i32 s55, s55, s31
	v_add_u32_e32 v198, s58, v207
	v_lshl_add_u64 v[202:203], s[24:25], 0, v[152:153]
	s_mov_b32 m0, s55
	ds_read_b128 v[186:189], v198
	ds_read_b128 v[190:193], v198 offset:1024
	ds_read_b128 v[194:197], v198 offset:2048
	ds_read_b128 v[198:201], v198 offset:3072
	global_load_lds_dwordx4 v[202:203], off
	s_add_i32 m0, s55, 0x2000
	v_lshl_add_u64 v[202:203], s[24:25], 0, v[156:157]
	global_load_lds_dwordx4 v[202:203], off
	s_barrier
	s_waitcnt lgkmcnt(3)
	v_mfma_f32_16x16x32_bf16 v[92:95], v[186:189], v[144:147], v[92:95]
	s_setprio 1
	s_waitcnt lgkmcnt(1)
	v_mfma_f32_16x16x32_bf16 v[88:91], v[194:197], v[144:147], v[88:91]
	s_mov_b32 m0, s33
	v_lshl_add_u64 v[202:203], s[26:27], 0, v[152:153]
	v_mfma_f32_16x16x32_bf16 v[84:87], v[186:189], v[162:165], v[84:87]
	v_mfma_f32_16x16x32_bf16 v[80:83], v[194:197], v[162:165], v[80:83]
	v_mfma_f32_16x16x32_bf16 v[76:79], v[186:189], v[170:173], v[76:79]
	v_mfma_f32_16x16x32_bf16 v[72:75], v[194:197], v[170:173], v[72:75]
	v_mfma_f32_16x16x32_bf16 v[68:71], v[186:189], v[178:181], v[68:71]
	v_mfma_f32_16x16x32_bf16 v[64:67], v[194:197], v[178:181], v[64:67]
	v_mfma_f32_16x16x32_bf16 v[92:95], v[190:193], v[148:151], v[92:95]
	s_waitcnt lgkmcnt(0)
	v_mfma_f32_16x16x32_bf16 v[88:91], v[198:201], v[148:151], v[88:91]
	v_mfma_f32_16x16x32_bf16 v[84:87], v[190:193], v[166:169], v[84:87]
	v_mfma_f32_16x16x32_bf16 v[80:83], v[198:201], v[166:169], v[80:83]
	v_mfma_f32_16x16x32_bf16 v[76:79], v[190:193], v[174:177], v[76:79]
	v_mfma_f32_16x16x32_bf16 v[72:75], v[198:201], v[174:177], v[72:75]
	v_mfma_f32_16x16x32_bf16 v[68:71], v[190:193], v[182:185], v[68:71]
	s_setprio 0
	v_mfma_f32_16x16x32_bf16 v[64:67], v[198:201], v[182:185], v[64:67]
	s_barrier
	ds_read_b128 v[144:147], v209 offset:16384
	ds_read_b128 v[148:151], v209 offset:17408
	ds_read_b128 v[162:165], v209 offset:18432
	ds_read_b128 v[166:169], v209 offset:19456
	ds_read_b128 v[170:173], v209 offset:20480
	ds_read_b128 v[174:177], v209 offset:21504
	ds_read_b128 v[178:181], v209 offset:22528
	ds_read_b128 v[182:185], v209 offset:23552
	global_load_lds_dwordx4 v[202:203], off
	s_mov_b32 m0, s34
	v_lshl_add_u64 v[202:203], s[26:27], 0, v[156:157]
	global_load_lds_dwordx4 v[202:203], off
	s_barrier
	s_waitcnt lgkmcnt(7)
	v_mfma_f32_16x16x32_bf16 v[60:63], v[128:131], v[144:147], v[60:63]
	s_setprio 1
	v_mfma_f32_16x16x32_bf16 v[56:59], v[136:139], v[144:147], v[56:59]
	s_waitcnt lgkmcnt(5)
	v_mfma_f32_16x16x32_bf16 v[52:55], v[128:131], v[162:165], v[52:55]
	v_mfma_f32_16x16x32_bf16 v[48:51], v[136:139], v[162:165], v[48:51]
	s_waitcnt lgkmcnt(3)
	v_mfma_f32_16x16x32_bf16 v[44:47], v[128:131], v[170:173], v[44:47]
	v_mfma_f32_16x16x32_bf16 v[40:43], v[136:139], v[170:173], v[40:43]
	s_waitcnt lgkmcnt(1)
	v_mfma_f32_16x16x32_bf16 v[36:39], v[128:131], v[178:181], v[36:39]
	v_mfma_f32_16x16x32_bf16 v[32:35], v[136:139], v[178:181], v[32:35]
	v_mfma_f32_16x16x32_bf16 v[60:63], v[132:135], v[148:151], v[60:63]
	v_mfma_f32_16x16x32_bf16 v[56:59], v[140:143], v[148:151], v[56:59]
	v_mfma_f32_16x16x32_bf16 v[52:55], v[132:135], v[166:169], v[52:55]
	v_mfma_f32_16x16x32_bf16 v[48:51], v[140:143], v[166:169], v[48:51]
	v_mfma_f32_16x16x32_bf16 v[44:47], v[132:135], v[174:177], v[44:47]
	v_mfma_f32_16x16x32_bf16 v[40:43], v[140:143], v[174:177], v[40:43]
	s_waitcnt lgkmcnt(0)
	v_mfma_f32_16x16x32_bf16 v[36:39], v[132:135], v[182:185], v[36:39]
	s_setprio 0
	v_mfma_f32_16x16x32_bf16 v[32:35], v[140:143], v[182:185], v[32:35]
	s_barrier
	s_add_u32 s56, s24, s52
	s_addc_u32 s57, s25, 0
	s_add_i32 s55, s58, s31
	s_mov_b32 m0, s55
	v_lshl_add_u64 v[128:129], s[56:57], 0, v[152:153]
	global_load_lds_dwordx4 v[128:129], off
	s_add_i32 m0, s55, 0x2000
	v_lshl_add_u64 v[128:129], s[56:57], 0, v[156:157]
	global_load_lds_dwordx4 v[128:129], off
	s_waitcnt vmcnt(6)
	s_barrier
	v_mfma_f32_16x16x32_bf16 v[28:31], v[186:189], v[144:147], v[28:31]
	s_setprio 1
	v_mfma_f32_16x16x32_bf16 v[24:27], v[194:197], v[144:147], v[24:27]
	s_add_i32 s55, 0, 0x18000
	v_add_u32_e32 v140, s55, v207
	v_mfma_f32_16x16x32_bf16 v[20:23], v[186:189], v[162:165], v[20:23]
	v_mfma_f32_16x16x32_bf16 v[16:19], v[194:197], v[162:165], v[16:19]
	v_mfma_f32_16x16x32_bf16 v[12:15], v[186:189], v[170:173], v[12:15]
	v_mfma_f32_16x16x32_bf16 v[8:11], v[194:197], v[170:173], v[8:11]
	v_mfma_f32_16x16x32_bf16 v[4:7], v[186:189], v[178:181], v[4:7]
	v_mfma_f32_16x16x32_bf16 v[0:3], v[194:197], v[178:181], v[0:3]
	v_mfma_f32_16x16x32_bf16 v[28:31], v[190:193], v[148:151], v[28:31]
	v_mfma_f32_16x16x32_bf16 v[24:27], v[198:201], v[148:151], v[24:27]
	v_mfma_f32_16x16x32_bf16 v[20:23], v[190:193], v[166:169], v[20:23]
	v_mfma_f32_16x16x32_bf16 v[16:19], v[198:201], v[166:169], v[16:19]
	v_mfma_f32_16x16x32_bf16 v[12:15], v[190:193], v[174:177], v[12:15]
	v_mfma_f32_16x16x32_bf16 v[8:11], v[198:201], v[174:177], v[8:11]
	v_mfma_f32_16x16x32_bf16 v[4:7], v[190:193], v[182:185], v[4:7]
	s_setprio 0
	v_mfma_f32_16x16x32_bf16 v[0:3], v[198:201], v[182:185], v[0:3]
	s_barrier
	ds_read_b128 v[128:131], v140
	ds_read_b128 v[132:135], v140 offset:1024
	ds_read_b128 v[136:139], v140 offset:2048
	ds_read_b128 v[140:143], v140 offset:3072
	s_add_u32 s26, s26, s52
	s_addc_u32 s27, s27, 0
	s_mov_b32 m0, s35
	v_lshl_add_u64 v[186:187], s[26:27], 0, v[152:153]
	ds_read_b128 v[144:147], v209 offset:32768
	ds_read_b128 v[148:151], v209 offset:33792
	ds_read_b128 v[162:165], v209 offset:34816
	ds_read_b128 v[166:169], v209 offset:35840
	ds_read_b128 v[170:173], v209 offset:36864
	ds_read_b128 v[174:177], v209 offset:37888
	ds_read_b128 v[178:181], v209 offset:38912
	ds_read_b128 v[182:185], v209 offset:39936
	global_load_lds_dwordx4 v[186:187], off
	s_mov_b32 m0, s36
	v_lshl_add_u64 v[186:187], s[26:27], 0, v[156:157]
	global_load_lds_dwordx4 v[186:187], off
	s_waitcnt lgkmcnt(8)
	s_barrier
; #define PG8_STAGE(bufoff, gbase, voff) do { _Pragma("unroll") for (int _i = 0; _i < 2; ++_i) \
;         __builtin_amdgcn_global_load_lds((const unsigned*)((const char*)(gbase) + (voff)[_i]), (LAS unsigned*)(lds + (bufoff) + ldsw + _i * 8192), 16, 0, 0); } while (0)
; #define PG8_LDA(dst, b, h) do { _Pragma("unroll") for (int m = 0; m < 4; ++m) _Pragma("unroll") for (int k = 0; k < 2; ++k) dst[m][k] = *(const LAS bf16x8*)(lds + PG8_SA(b, h) + aoff + m * 2048 + k * 1024); } while (0)
; #define PG8_LDB(dst, b, h) do { _Pragma("unroll") for (int n = 0; n < 2; ++n) _Pragma("unroll") for (int k = 0; k < 2; ++k) dst[n][k] = *(const LAS bf16x8*)(lds + PG8_SB(b, h) + boff + n * 2048 + k * 1024); } while (0)
; #define PG8_MMA(ai, bj, At, Bt) do { __builtin_amdgcn_s_setprio(1); _Pragma("unroll") for (int m = 0; m < 4; ++m) _Pragma("unroll") for (int n = 0; n < 2; ++n) _Pragma("unroll") for (int k = 0; k < 2; ++k) \
;         acc[ai][bj][m][n] = __builtin_amdgcn_mfma_f32_16x16x32_bf16(Bt[n][k], At[m][k], acc[ai][bj][m][n], 0, 0, 0); __builtin_amdgcn_s_setprio(0); } while (0)
; #define PG8_WAIT_V(n) asm volatile("s_waitcnt vmcnt(" #n ")" ::: "memory")
; #define PG8_WAIT_L(n) asm volatile("s_waitcnt lgkmcnt(" #n ")" ::: "memory")
; #define PG8_BAR __builtin_amdgcn_s_barrier()
; #define PG8_SCHED __builtin_amdgcn_sched_barrier(0)
; template <class Epi>
; __device__ __forceinline__ void gemm_phase(LAS unsigned char* lds, const Gemm g, const StaticOrder& S, const Epi& E) {
;     ...
;             PG8_WAIT_L(8); PG8_BAR; PG8_WAIT_L(0); PG8_MMA(0, 0, At, B0); PG8_BAR; PG8_SCHED;
;             PG8_LDB(B1, 1, 1); PG8_STAGE(PG8_SB(1, 0), b3, voffB);
;             PG8_BAR; PG8_WAIT_L(0); PG8_MMA(0, 1, At, B1); PG8_BAR;
;             PG8_LDA(At, 1, 1); PG8_STAGE(PG8_SA(1, 0), a3, voffA);
;             PG8_BAR; PG8_WAIT_L(0); PG8_MMA(1, 0, At, B0); PG8_BAR; PG8_SCHED;
;             PG8_STAGE(PG8_SB(1, 1), b3 + hstepB, voffB);
;             PG8_WAIT_V(6); PG8_BAR; PG8_MMA(1, 1, At, B1); PG8_BAR;
	s_waitcnt lgkmcnt(7)
	v_mfma_f32_16x16x32_bf16 v[124:127], v[128:131], v[144:147], v[124:127]
	s_setprio 1
	v_mfma_f32_16x16x32_bf16 v[120:123], v[136:139], v[144:147], v[120:123]
	s_waitcnt lgkmcnt(5)
	v_mfma_f32_16x16x32_bf16 v[116:119], v[128:131], v[162:165], v[116:119]
	v_mfma_f32_16x16x32_bf16 v[112:115], v[136:139], v[162:165], v[112:115]
	s_waitcnt lgkmcnt(3)
	v_mfma_f32_16x16x32_bf16 v[108:111], v[128:131], v[170:173], v[108:111]
	v_mfma_f32_16x16x32_bf16 v[104:107], v[136:139], v[170:173], v[104:107]
	s_waitcnt lgkmcnt(1)
	v_mfma_f32_16x16x32_bf16 v[100:103], v[128:131], v[178:181], v[100:103]
	v_mfma_f32_16x16x32_bf16 v[96:99], v[136:139], v[178:181], v[96:99]
	v_mfma_f32_16x16x32_bf16 v[124:127], v[132:135], v[148:151], v[124:127]
	v_mfma_f32_16x16x32_bf16 v[120:123], v[140:143], v[148:151], v[120:123]
	v_mfma_f32_16x16x32_bf16 v[116:119], v[132:135], v[166:169], v[116:119]
	v_mfma_f32_16x16x32_bf16 v[112:115], v[140:143], v[166:169], v[112:115]
	v_mfma_f32_16x16x32_bf16 v[108:111], v[132:135], v[174:177], v[108:111]
	v_mfma_f32_16x16x32_bf16 v[104:107], v[140:143], v[174:177], v[104:107]
	s_waitcnt lgkmcnt(0)
	v_mfma_f32_16x16x32_bf16 v[100:103], v[132:135], v[182:185], v[100:103]
	s_setprio 0
	v_mfma_f32_16x16x32_bf16 v[96:99], v[140:143], v[182:185], v[96:99]
	s_barrier
	s_add_i32 s26, 0, 0x1c000
	s_add_u32 s24, s24, 0x4000
	s_addc_u32 s25, s25, 0
	s_add_i32 s27, s55, s31
	v_add_u32_e32 v198, s26, v207
	v_lshl_add_u64 v[202:203], s[24:25], 0, v[152:153]
	s_mov_b32 m0, s27
	ds_read_b128 v[186:189], v198
	ds_read_b128 v[190:193], v198 offset:1024
	ds_read_b128 v[194:197], v198 offset:2048
	ds_read_b128 v[198:201], v198 offset:3072
	global_load_lds_dwordx4 v[202:203], off
	s_add_i32 m0, s27, 0x2000
	v_lshl_add_u64 v[202:203], s[24:25], 0, v[156:157]
	global_load_lds_dwordx4 v[202:203], off
	s_barrier
	s_waitcnt lgkmcnt(3)
	v_mfma_f32_16x16x32_bf16 v[92:95], v[186:189], v[144:147], v[92:95]
	s_setprio 1
	s_waitcnt lgkmcnt(1)
	v_mfma_f32_16x16x32_bf16 v[88:91], v[194:197], v[144:147], v[88:91]
	s_mov_b32 m0, s38
	v_lshl_add_u64 v[202:203], s[22:23], 0, v[152:153]
	v_mfma_f32_16x16x32_bf16 v[84:87], v[186:189], v[162:165], v[84:87]
	v_mfma_f32_16x16x32_bf16 v[80:83], v[194:197], v[162:165], v[80:83]
	v_mfma_f32_16x16x32_bf16 v[76:79], v[186:189], v[170:173], v[76:79]
	v_mfma_f32_16x16x32_bf16 v[72:75], v[194:197], v[170:173], v[72:75]
	v_mfma_f32_16x16x32_bf16 v[68:71], v[186:189], v[178:181], v[68:71]
	v_mfma_f32_16x16x32_bf16 v[64:67], v[194:197], v[178:181], v[64:67]
	v_mfma_f32_16x16x32_bf16 v[92:95], v[190:193], v[148:151], v[92:95]
	s_waitcnt lgkmcnt(0)
	v_mfma_f32_16x16x32_bf16 v[88:91], v[198:201], v[148:151], v[88:91]
	v_mfma_f32_16x16x32_bf16 v[84:87], v[190:193], v[166:169], v[84:87]
	v_mfma_f32_16x16x32_bf16 v[80:83], v[198:201], v[166:169], v[80:83]
	v_mfma_f32_16x16x32_bf16 v[76:79], v[190:193], v[174:177], v[76:79]
	v_mfma_f32_16x16x32_bf16 v[72:75], v[198:201], v[174:177], v[72:75]
	v_mfma_f32_16x16x32_bf16 v[68:71], v[190:193], v[182:185], v[68:71]
	s_setprio 0
	v_mfma_f32_16x16x32_bf16 v[64:67], v[198:201], v[182:185], v[64:67]
	s_barrier
	ds_read_b128 v[144:147], v209 offset:49152
	ds_read_b128 v[148:151], v209 offset:50176
	ds_read_b128 v[162:165], v209 offset:51200
	ds_read_b128 v[166:169], v209 offset:52224
	ds_read_b128 v[170:173], v209 offset:53248
	ds_read_b128 v[174:177], v209 offset:54272
	ds_read_b128 v[178:181], v209 offset:55296
	ds_read_b128 v[182:185], v209 offset:56320
	global_load_lds_dwordx4 v[202:203], off
	s_mov_b32 m0, s39
	v_lshl_add_u64 v[202:203], s[22:23], 0, v[156:157]
	global_load_lds_dwordx4 v[202:203], off
	s_barrier
	s_waitcnt lgkmcnt(7)
	v_mfma_f32_16x16x32_bf16 v[60:63], v[128:131], v[144:147], v[60:63]
	s_setprio 1
	v_mfma_f32_16x16x32_bf16 v[56:59], v[136:139], v[144:147], v[56:59]
	s_waitcnt lgkmcnt(5)
	v_mfma_f32_16x16x32_bf16 v[52:55], v[128:131], v[162:165], v[52:55]
	v_mfma_f32_16x16x32_bf16 v[48:51], v[136:139], v[162:165], v[48:51]
	s_waitcnt lgkmcnt(3)
	v_mfma_f32_16x16x32_bf16 v[44:47], v[128:131], v[170:173], v[44:47]
	v_mfma_f32_16x16x32_bf16 v[40:43], v[136:139], v[170:173], v[40:43]
	s_waitcnt lgkmcnt(1)
	v_mfma_f32_16x16x32_bf16 v[36:39], v[128:131], v[178:181], v[36:39]
	v_mfma_f32_16x16x32_bf16 v[32:35], v[136:139], v[178:181], v[32:35]
	v_mfma_f32_16x16x32_bf16 v[60:63], v[132:135], v[148:151], v[60:63]
	v_mfma_f32_16x16x32_bf16 v[56:59], v[140:143], v[148:151], v[56:59]
	v_mfma_f32_16x16x32_bf16 v[52:55], v[132:135], v[166:169], v[52:55]
	v_mfma_f32_16x16x32_bf16 v[48:51], v[140:143], v[166:169], v[48:51]
	v_mfma_f32_16x16x32_bf16 v[44:47], v[132:135], v[174:177], v[44:47]
	v_mfma_f32_16x16x32_bf16 v[40:43], v[140:143], v[174:177], v[40:43]
	s_waitcnt lgkmcnt(0)
	v_mfma_f32_16x16x32_bf16 v[36:39], v[132:135], v[182:185], v[36:39]
	s_setprio 0
	v_mfma_f32_16x16x32_bf16 v[32:35], v[140:143], v[182:185], v[32:35]
	s_barrier
	s_add_u32 s22, s24, s52
	s_addc_u32 s23, s25, 0
	s_add_i32 s24, s26, s31
	s_mov_b32 m0, s24
	v_lshl_add_u64 v[128:129], s[22:23], 0, v[152:153]
	global_load_lds_dwordx4 v[128:129], off
	s_add_i32 m0, s24, 0x2000
	v_lshl_add_u64 v[128:129], s[22:23], 0, v[156:157]
	global_load_lds_dwordx4 v[128:129], off
	s_waitcnt vmcnt(6)
	s_barrier
	v_mfma_f32_16x16x32_bf16 v[28:31], v[186:189], v[144:147], v[28:31]
	s_setprio 1
	v_mfma_f32_16x16x32_bf16 v[24:27], v[194:197], v[144:147], v[24:27]
	s_add_u32 s4, s4, 0x8000
	s_addc_u32 s5, s5, 0
	s_add_u32 s50, s50, 0x8000
	s_addc_u32 s51, s51, 0
	v_mfma_f32_16x16x32_bf16 v[20:23], v[186:189], v[162:165], v[20:23]
	v_mfma_f32_16x16x32_bf16 v[16:19], v[194:197], v[162:165], v[16:19]
	v_mfma_f32_16x16x32_bf16 v[12:15], v[186:189], v[170:173], v[12:15]
	v_mfma_f32_16x16x32_bf16 v[8:11], v[194:197], v[170:173], v[8:11]
	v_mfma_f32_16x16x32_bf16 v[4:7], v[186:189], v[178:181], v[4:7]
	v_mfma_f32_16x16x32_bf16 v[0:3], v[194:197], v[178:181], v[0:3]
	v_mfma_f32_16x16x32_bf16 v[28:31], v[190:193], v[148:151], v[28:31]
	v_mfma_f32_16x16x32_bf16 v[24:27], v[198:201], v[148:151], v[24:27]
	v_mfma_f32_16x16x32_bf16 v[20:23], v[190:193], v[166:169], v[20:23]
	v_mfma_f32_16x16x32_bf16 v[16:19], v[198:201], v[166:169], v[16:19]
	v_mfma_f32_16x16x32_bf16 v[12:15], v[190:193], v[174:177], v[12:15]
	v_mfma_f32_16x16x32_bf16 v[8:11], v[198:201], v[174:177], v[8:11]
	v_mfma_f32_16x16x32_bf16 v[4:7], v[190:193], v[182:185], v[4:7]
	s_cmp_ge_u32 s54, s28
	s_mov_b32 s22, s54
	s_setprio 0
	v_mfma_f32_16x16x32_bf16 v[0:3], v[198:201], v[182:185], v[0:3]
	s_barrier
	s_cbranch_scc0 .LBB0_187

; #define PG8_STAGE(bufoff, gbase, voff) do { _Pragma("unroll") for (int _i = 0; _i < 2; ++_i) \
;         __builtin_amdgcn_global_load_lds((const unsigned*)((const char*)(gbase) + (voff)[_i]), (LAS unsigned*)(lds + (bufoff) + ldsw + _i * 8192), 16, 0, 0); } while (0)
; #define PG8_LDA(dst, b, h) do { _Pragma("unroll") for (int m = 0; m < 4; ++m) _Pragma("unroll") for (int k = 0; k < 2; ++k) dst[m][k] = *(const LAS bf16x8*)(lds + PG8_SA(b, h) + aoff + m * 2048 + k * 1024); } while (0)
; #define PG8_LDB(dst, b, h) do { _Pragma("unroll") for (int n = 0; n < 2; ++n) _Pragma("unroll") for (int k = 0; k < 2; ++k) dst[n][k] = *(const LAS bf16x8*)(lds + PG8_SB(b, h) + boff + n * 2048 + k * 1024); } while (0)
; template <class Epi>
; __device__ __forceinline__ void gemm_phase(LAS unsigned char* lds, const Gemm g, const StaticOrder& S, const Epi& E) {
;     ...
;         const bool has_next = S.next(ui + 1, nxt);
;         const char* nA = has_next ? (const char*)g.A + (size_t)nxt.pm * tstepA : cA; const char* nB = has_next ? (const char*)g.Bt + (size_t)nxt.pn * tstepB : cB;
;         for (int t = 0; t < nt; t += 2) {
;             const bool last = (t == nt - 2);
;             const char* a1 = cA + (size_t)(t + 1) * kstep;
;             const char* a2 = last ? nA : cA + (size_t)(t + 2) * kstep; const char* b2 = last ? nB : cB + (size_t)(t + 2) * kstep;
;             const char* a3 = a2 + kstep; const char* b3 = b2 + kstep;
;             PG8_LDB(B0, 0, 0); PG8_SCHED; PG8_LDA(At, 0, 0); PG8_STAGE(PG8_SA(1, 1), a1 + hstepA, voffA);
;             PG8_WAIT_L(8); PG8_BAR; PG8_WAIT_L(0); PG8_MMA(0, 0, At, B0); PG8_BAR; PG8_SCHED;
;             PG8_LDB(B1, 0, 1); PG8_STAGE(PG8_SB(0, 0), b2, voffB);
;             PG8_BAR; PG8_WAIT_L(0); PG8_MMA(0, 1, At, B1); PG8_BAR;
;             PG8_LDA(At, 0, 1); PG8_STAGE(PG8_SA(0, 0), a2, voffA);
;             PG8_BAR; PG8_WAIT_L(0); PG8_MMA(1, 0, At, B0); PG8_BAR; PG8_SCHED;
;             PG8_STAGE(PG8_SB(0, 1), b2 + hstepB, voffB);
;             PG8_WAIT_V(6); PG8_BAR; PG8_MMA(1, 1, At, B1); PG8_BAR;
;             PG8_LDB(B0, 1, 0); PG8_SCHED; PG8_LDA(At, 1, 0); PG8_STAGE(PG8_SA(0, 1), a2 + hstepA, voffA);
;             PG8_WAIT_L(8); PG8_BAR; PG8_WAIT_L(0); PG8_MMA(0, 0, At, B0); PG8_BAR; PG8_SCHED;
;             PG8_LDB(B1, 1, 1); PG8_STAGE(PG8_SB(1, 0), b3, voffB);
;             PG8_BAR; PG8_WAIT_L(0); PG8_MMA(0, 1, At, B1); PG8_BAR;
.LBB0_246:
	s_ashr_i32 s5, s4, 31
	v_cmp_lt_i64_e32 vcc, s[6:7], v[154:155]
	s_lshl_b64 s[6:7], s[4:5], 20
	v_readlane_b32 s8, v252, 53
	v_readlane_b32 s9, v252, 54
	s_add_u32 s6, s8, s6
	s_addc_u32 s7, s9, s7
	s_and_b64 s[8:9], vcc, exec
	s_cselect_b32 s5, s7, s13
	s_cselect_b32 s11, s6, s12
	s_ashr_i32 s3, s2, 31
	s_lshl_b64 s[8:9], s[2:3], 20
	s_add_u32 s8, s21, s8
	s_addc_u32 s9, s22, s9
	s_and_b64 s[16:17], vcc, exec
	s_cselect_b32 s3, s9, s15
	s_cselect_b32 s35, s8, s14
	s_add_u32 s12, s12, 0x84000
	s_addc_u32 s13, s13, 0
	s_add_u32 s36, s14, 0x8000
	s_addc_u32 s37, s15, 0
	s_mov_b32 s38, -2
	s_add_u32 s14, s12, 0xfff84000
	s_addc_u32 s15, s13, -1
	s_cmp_eq_u32 s38, 28
	s_cselect_b32 s18, s11, s14
	s_cselect_b32 s19, s5, s15
	s_cselect_b32 s14, s35, s36
	s_cselect_b32 s15, s3, s37
	s_add_u32 s16, s18, 0x4000
	s_addc_u32 s17, s19, 0
	s_add_i32 s39, 0, 0x10000
	v_add_u32_e32 v140, s39, v170
	ds_read_b128 v[128:131], v140
	ds_read_b128 v[132:135], v140 offset:1024
	ds_read_b128 v[136:139], v140 offset:2048
	ds_read_b128 v[140:143], v140 offset:3072
	v_lshl_add_u64 v[194:195], s[12:13], 0, v[156:157]
	s_add_i32 m0, s25, 0xc000
	ds_read_b128 v[144:147], v172
	ds_read_b128 v[148:151], v172 offset:1024
	ds_read_b128 v[166:169], v172 offset:2048
	ds_read_b128 v[174:177], v172 offset:3072
	ds_read_b128 v[178:181], v172 offset:4096
	ds_read_b128 v[182:185], v172 offset:5120
	ds_read_b128 v[186:189], v172 offset:6144
	ds_read_b128 v[190:193], v172 offset:7168
	global_load_lds_dwordx4 v[194:195], off
	s_add_i32 m0, s25, 0xe000
	v_lshl_add_u64 v[194:195], s[12:13], 0, v[158:159]
	global_load_lds_dwordx4 v[194:195], off
	s_waitcnt lgkmcnt(8)
	s_barrier
	s_waitcnt lgkmcnt(7)
	v_mfma_f32_16x16x32_bf16 v[124:127], v[128:131], v[144:147], 0
	s_setprio 1
	v_mfma_f32_16x16x32_bf16 v[120:123], v[136:139], v[144:147], 0
	s_waitcnt lgkmcnt(5)
	v_mfma_f32_16x16x32_bf16 v[108:111], v[128:131], v[166:169], 0
	v_mfma_f32_16x16x32_bf16 v[104:107], v[136:139], v[166:169], 0
	s_waitcnt lgkmcnt(3)
	v_mfma_f32_16x16x32_bf16 v[92:95], v[128:131], v[178:181], 0
	v_mfma_f32_16x16x32_bf16 v[88:91], v[136:139], v[178:181], 0
	s_waitcnt lgkmcnt(1)
	v_mfma_f32_16x16x32_bf16 v[76:79], v[128:131], v[186:189], 0
	v_mfma_f32_16x16x32_bf16 v[72:75], v[136:139], v[186:189], 0
	v_mfma_f32_16x16x32_bf16 v[124:127], v[132:135], v[148:151], v[124:127]
	v_mfma_f32_16x16x32_bf16 v[120:123], v[140:143], v[148:151], v[120:123]
	v_mfma_f32_16x16x32_bf16 v[108:111], v[132:135], v[174:177], v[108:111]
	v_mfma_f32_16x16x32_bf16 v[104:107], v[140:143], v[174:177], v[104:107]
	v_mfma_f32_16x16x32_bf16 v[92:95], v[132:135], v[182:185], v[92:95]
	v_mfma_f32_16x16x32_bf16 v[88:91], v[140:143], v[182:185], v[88:91]
	s_waitcnt lgkmcnt(0)
	v_mfma_f32_16x16x32_bf16 v[76:79], v[132:135], v[190:193], v[76:79]
	s_setprio 0
	v_mfma_f32_16x16x32_bf16 v[72:75], v[140:143], v[190:193], v[72:75]
	s_barrier
	s_add_i32 s42, 0, 0x14000
	s_add_i32 s39, s39, s23
	v_add_u32_e32 v152, s42, v170
	v_lshl_add_u64 v[210:211], s[14:15], 0, v[156:157]
	s_mov_b32 m0, s39
	ds_read_b128 v[194:197], v152
	ds_read_b128 v[198:201], v152 offset:1024
	ds_read_b128 v[202:205], v152 offset:2048
	ds_read_b128 v[206:209], v152 offset:3072
	global_load_lds_dwordx4 v[210:211], off
	s_add_i32 m0, s39, 0x2000
	v_lshl_add_u64 v[210:211], s[14:15], 0, v[158:159]
	global_load_lds_dwordx4 v[210:211], off
	s_barrier
	s_waitcnt lgkmcnt(3)
	v_mfma_f32_16x16x32_bf16 v[116:119], v[194:197], v[144:147], 0
	s_setprio 1
	s_waitcnt lgkmcnt(1)
	v_mfma_f32_16x16x32_bf16 v[112:115], v[202:205], v[144:147], 0
	s_mov_b32 m0, s25
	v_lshl_add_u64 v[210:211], s[18:19], 0, v[156:157]
	v_mfma_f32_16x16x32_bf16 v[100:103], v[194:197], v[166:169], 0
	v_mfma_f32_16x16x32_bf16 v[96:99], v[202:205], v[166:169], 0
	v_mfma_f32_16x16x32_bf16 v[84:87], v[194:197], v[178:181], 0
	v_mfma_f32_16x16x32_bf16 v[80:83], v[202:205], v[178:181], 0
	v_mfma_f32_16x16x32_bf16 v[68:71], v[194:197], v[186:189], 0
	v_mfma_f32_16x16x32_bf16 v[64:67], v[202:205], v[186:189], 0
	v_mfma_f32_16x16x32_bf16 v[116:119], v[198:201], v[148:151], v[116:119]
	s_waitcnt lgkmcnt(0)
	v_mfma_f32_16x16x32_bf16 v[112:115], v[206:209], v[148:151], v[112:115]
	v_mfma_f32_16x16x32_bf16 v[100:103], v[198:201], v[174:177], v[100:103]
	v_mfma_f32_16x16x32_bf16 v[96:99], v[206:209], v[174:177], v[96:99]
	v_mfma_f32_16x16x32_bf16 v[84:87], v[198:201], v[182:185], v[84:87]
	v_mfma_f32_16x16x32_bf16 v[80:83], v[206:209], v[182:185], v[80:83]
	v_mfma_f32_16x16x32_bf16 v[68:71], v[198:201], v[190:193], v[68:71]
	s_setprio 0
	v_mfma_f32_16x16x32_bf16 v[64:67], v[206:209], v[190:193], v[64:67]
	s_barrier
	ds_read_b128 v[144:147], v172 offset:16384
	ds_read_b128 v[148:151], v172 offset:17408
	ds_read_b128 v[166:169], v172 offset:18432
	ds_read_b128 v[174:177], v172 offset:19456
	ds_read_b128 v[178:181], v172 offset:20480
	ds_read_b128 v[182:185], v172 offset:21504
	ds_read_b128 v[186:189], v172 offset:22528
	ds_read_b128 v[190:193], v172 offset:23552
	global_load_lds_dwordx4 v[210:211], off
	s_mov_b32 m0, s26
	v_lshl_add_u64 v[210:211], s[18:19], 0, v[158:159]
	global_load_lds_dwordx4 v[210:211], off
	s_barrier
; #define PG8_STAGE(bufoff, gbase, voff) do { _Pragma("unroll") for (int _i = 0; _i < 2; ++_i) \
;         __builtin_amdgcn_global_load_lds((const unsigned*)((const char*)(gbase) + (voff)[_i]), (LAS unsigned*)(lds + (bufoff) + ldsw + _i * 8192), 16, 0, 0); } while (0)
; #define PG8_LDA(dst, b, h) do { _Pragma("unroll") for (int m = 0; m < 4; ++m) _Pragma("unroll") for (int k = 0; k < 2; ++k) dst[m][k] = *(const LAS bf16x8*)(lds + PG8_SA(b, h) + aoff + m * 2048 + k * 1024); } while (0)
; #define PG8_LDB(dst, b, h) do { _Pragma("unroll") for (int n = 0; n < 2; ++n) _Pragma("unroll") for (int k = 0; k < 2; ++k) dst[n][k] = *(const LAS bf16x8*)(lds + PG8_SB(b, h) + boff + n * 2048 + k * 1024); } while (0)
; #define PG8_MMA(ai, bj, At, Bt) do { __builtin_amdgcn_s_setprio(1); _Pragma("unroll") for (int m = 0; m < 4; ++m) _Pragma("unroll") for (int n = 0; n < 2; ++n) _Pragma("unroll") for (int k = 0; k < 2; ++k) \
;         acc[ai][bj][m][n] = __builtin_amdgcn_mfma_f32_16x16x32_bf16(Bt[n][k], At[m][k], acc[ai][bj][m][n], 0, 0, 0); __builtin_amdgcn_s_setprio(0); } while (0)
; #define PG8_WAIT_V(n) asm volatile("s_waitcnt vmcnt(" #n ")" ::: "memory")
; #define PG8_WAIT_L(n) asm volatile("s_waitcnt lgkmcnt(" #n ")" ::: "memory")
; #define PG8_BAR __builtin_amdgcn_s_barrier()
; #define PG8_SCHED __builtin_amdgcn_sched_barrier(0)
; template <class Epi>
; __device__ __forceinline__ void gemm_phase(LAS unsigned char* lds, const Gemm g, const StaticOrder& S, const Epi& E) {
;     ...
;             PG8_LDA(At, 0, 1); PG8_STAGE(PG8_SA(0, 0), a2, voffA);
;             PG8_BAR; PG8_WAIT_L(0); PG8_MMA(1, 0, At, B0); PG8_BAR; PG8_SCHED;
;             PG8_STAGE(PG8_SB(0, 1), b2 + hstepB, voffB);
;             PG8_WAIT_V(6); PG8_BAR; PG8_MMA(1, 1, At, B1); PG8_BAR;
;             PG8_LDB(B0, 1, 0); PG8_SCHED; PG8_LDA(At, 1, 0); PG8_STAGE(PG8_SA(0, 1), a2 + hstepA, voffA);
;             PG8_WAIT_L(8); PG8_BAR; PG8_WAIT_L(0); PG8_MMA(0, 0, At, B0); PG8_BAR; PG8_SCHED;
;             PG8_LDB(B1, 1, 1); PG8_STAGE(PG8_SB(1, 0), b3, voffB);
;             PG8_BAR; PG8_WAIT_L(0); PG8_MMA(0, 1, At, B1); PG8_BAR;
	s_waitcnt lgkmcnt(7)
	v_mfma_f32_16x16x32_bf16 v[60:63], v[128:131], v[144:147], 0
	s_setprio 1
	v_mfma_f32_16x16x32_bf16 v[56:59], v[136:139], v[144:147], 0
	s_waitcnt lgkmcnt(5)
	v_mfma_f32_16x16x32_bf16 v[44:47], v[128:131], v[166:169], 0
	v_mfma_f32_16x16x32_bf16 v[40:43], v[136:139], v[166:169], 0
	s_waitcnt lgkmcnt(3)
	v_mfma_f32_16x16x32_bf16 v[28:31], v[128:131], v[178:181], 0
	v_mfma_f32_16x16x32_bf16 v[24:27], v[136:139], v[178:181], 0
	s_waitcnt lgkmcnt(1)
	v_mfma_f32_16x16x32_bf16 v[12:15], v[128:131], v[186:189], 0
	v_mfma_f32_16x16x32_bf16 v[8:11], v[136:139], v[186:189], 0
	v_mfma_f32_16x16x32_bf16 v[60:63], v[132:135], v[148:151], v[60:63]
	v_mfma_f32_16x16x32_bf16 v[56:59], v[140:143], v[148:151], v[56:59]
	v_mfma_f32_16x16x32_bf16 v[44:47], v[132:135], v[174:177], v[44:47]
	v_mfma_f32_16x16x32_bf16 v[40:43], v[140:143], v[174:177], v[40:43]
	v_mfma_f32_16x16x32_bf16 v[28:31], v[132:135], v[182:185], v[28:31]
	v_mfma_f32_16x16x32_bf16 v[24:27], v[140:143], v[182:185], v[24:27]
	s_waitcnt lgkmcnt(0)
	v_mfma_f32_16x16x32_bf16 v[12:15], v[132:135], v[190:193], v[12:15]
	s_setprio 0
	v_mfma_f32_16x16x32_bf16 v[8:11], v[140:143], v[190:193], v[8:11]
	s_barrier
	s_add_u32 s40, s14, 0x80000
	s_addc_u32 s41, s15, 0
	s_add_i32 s39, s42, s23
	s_mov_b32 m0, s39
	v_lshl_add_u64 v[128:129], s[40:41], 0, v[156:157]
	global_load_lds_dwordx4 v[128:129], off
	s_add_i32 m0, s39, 0x2000
	v_lshl_add_u64 v[128:129], s[40:41], 0, v[158:159]
	global_load_lds_dwordx4 v[128:129], off
	s_waitcnt vmcnt(6)
	s_barrier
	v_mfma_f32_16x16x32_bf16 v[52:55], v[194:197], v[144:147], 0
	s_setprio 1
	v_mfma_f32_16x16x32_bf16 v[48:51], v[202:205], v[144:147], 0
	s_add_i32 s39, 0, 0x18000
	v_add_u32_e32 v140, s39, v170
	v_mfma_f32_16x16x32_bf16 v[36:39], v[194:197], v[166:169], 0
	v_mfma_f32_16x16x32_bf16 v[32:35], v[202:205], v[166:169], 0
	v_mfma_f32_16x16x32_bf16 v[20:23], v[194:197], v[178:181], 0
	v_mfma_f32_16x16x32_bf16 v[16:19], v[202:205], v[178:181], 0
	v_mfma_f32_16x16x32_bf16 v[4:7], v[194:197], v[186:189], 0
	v_mfma_f32_16x16x32_bf16 v[0:3], v[202:205], v[186:189], 0
	v_mfma_f32_16x16x32_bf16 v[52:55], v[198:201], v[148:151], v[52:55]
	v_mfma_f32_16x16x32_bf16 v[48:51], v[206:209], v[148:151], v[48:51]
	v_mfma_f32_16x16x32_bf16 v[36:39], v[198:201], v[174:177], v[36:39]
	v_mfma_f32_16x16x32_bf16 v[32:35], v[206:209], v[174:177], v[32:35]
	v_mfma_f32_16x16x32_bf16 v[20:23], v[198:201], v[182:185], v[20:23]
	v_mfma_f32_16x16x32_bf16 v[16:19], v[206:209], v[182:185], v[16:19]
	v_mfma_f32_16x16x32_bf16 v[4:7], v[198:201], v[190:193], v[4:7]
	s_setprio 0
	v_mfma_f32_16x16x32_bf16 v[0:3], v[206:209], v[190:193], v[0:3]
	s_barrier
	ds_read_b128 v[128:131], v140
	ds_read_b128 v[132:135], v140 offset:1024
	ds_read_b128 v[136:139], v140 offset:2048
	ds_read_b128 v[140:143], v140 offset:3072
	s_add_u32 s18, s18, 0x80000
	s_addc_u32 s19, s19, 0
	s_mov_b32 m0, s27
	v_lshl_add_u64 v[194:195], s[18:19], 0, v[156:157]
	ds_read_b128 v[144:147], v172 offset:32768
	ds_read_b128 v[148:151], v172 offset:33792
	ds_read_b128 v[166:169], v172 offset:34816
	ds_read_b128 v[174:177], v172 offset:35840
	ds_read_b128 v[178:181], v172 offset:36864
	ds_read_b128 v[182:185], v172 offset:37888
	ds_read_b128 v[186:189], v172 offset:38912
	ds_read_b128 v[190:193], v172 offset:39936
	global_load_lds_dwordx4 v[194:195], off
	s_mov_b32 m0, s28
	v_lshl_add_u64 v[194:195], s[18:19], 0, v[158:159]
	global_load_lds_dwordx4 v[194:195], off
	s_waitcnt lgkmcnt(8)
	s_barrier
	s_waitcnt lgkmcnt(7)
	v_mfma_f32_16x16x32_bf16 v[124:127], v[128:131], v[144:147], v[124:127]
	s_setprio 1
	v_mfma_f32_16x16x32_bf16 v[120:123], v[136:139], v[144:147], v[120:123]
	s_waitcnt lgkmcnt(5)
	v_mfma_f32_16x16x32_bf16 v[108:111], v[128:131], v[166:169], v[108:111]
	v_mfma_f32_16x16x32_bf16 v[104:107], v[136:139], v[166:169], v[104:107]
	s_waitcnt lgkmcnt(3)
	v_mfma_f32_16x16x32_bf16 v[92:95], v[128:131], v[178:181], v[92:95]
	v_mfma_f32_16x16x32_bf16 v[88:91], v[136:139], v[178:181], v[88:91]
	s_waitcnt lgkmcnt(1)
	v_mfma_f32_16x16x32_bf16 v[76:79], v[128:131], v[186:189], v[76:79]
	v_mfma_f32_16x16x32_bf16 v[72:75], v[136:139], v[186:189], v[72:75]
	v_mfma_f32_16x16x32_bf16 v[124:127], v[132:135], v[148:151], v[124:127]
	v_mfma_f32_16x16x32_bf16 v[120:123], v[140:143], v[148:151], v[120:123]
	v_mfma_f32_16x16x32_bf16 v[108:111], v[132:135], v[174:177], v[108:111]
	v_mfma_f32_16x16x32_bf16 v[104:107], v[140:143], v[174:177], v[104:107]
	v_mfma_f32_16x16x32_bf16 v[92:95], v[132:135], v[182:185], v[92:95]
	v_mfma_f32_16x16x32_bf16 v[88:91], v[140:143], v[182:185], v[88:91]
	s_waitcnt lgkmcnt(0)
	v_mfma_f32_16x16x32_bf16 v[76:79], v[132:135], v[190:193], v[76:79]
	s_setprio 0
	v_mfma_f32_16x16x32_bf16 v[72:75], v[140:143], v[190:193], v[72:75]
	s_barrier
	s_add_i32 s40, 0, 0x1c000
	s_add_u32 s18, s14, 0x4000
	s_addc_u32 s19, s15, 0
	s_add_i32 s39, s39, s23
	v_add_u32_e32 v152, s40, v170
	v_lshl_add_u64 v[210:211], s[18:19], 0, v[156:157]
	s_mov_b32 m0, s39
	ds_read_b128 v[194:197], v152
	ds_read_b128 v[198:201], v152 offset:1024
	ds_read_b128 v[202:205], v152 offset:2048
	ds_read_b128 v[206:209], v152 offset:3072
	global_load_lds_dwordx4 v[210:211], off
	s_add_i32 m0, s39, 0x2000
	v_lshl_add_u64 v[210:211], s[18:19], 0, v[158:159]
	global_load_lds_dwordx4 v[210:211], off
	s_barrier
; #define PG8_STAGE(bufoff, gbase, voff) do { _Pragma("unroll") for (int _i = 0; _i < 2; ++_i) \
;         __builtin_amdgcn_global_load_lds((const unsigned*)((const char*)(gbase) + (voff)[_i]), (LAS unsigned*)(lds + (bufoff) + ldsw + _i * 8192), 16, 0, 0); } while (0)
; #define PG8_LDA(dst, b, h) do { _Pragma("unroll") for (int m = 0; m < 4; ++m) _Pragma("unroll") for (int k = 0; k < 2; ++k) dst[m][k] = *(const LAS bf16x8*)(lds + PG8_SA(b, h) + aoff + m * 2048 + k * 1024); } while (0)
; #define PG8_LDB(dst, b, h) do { _Pragma("unroll") for (int n = 0; n < 2; ++n) _Pragma("unroll") for (int k = 0; k < 2; ++k) dst[n][k] = *(const LAS bf16x8*)(lds + PG8_SB(b, h) + boff + n * 2048 + k * 1024); } while (0)
; #define PG8_MMA(ai, bj, At, Bt) do { __builtin_amdgcn_s_setprio(1); _Pragma("unroll") for (int m = 0; m < 4; ++m) _Pragma("unroll") for (int n = 0; n < 2; ++n) _Pragma("unroll") for (int k = 0; k < 2; ++k) \
;         acc[ai][bj][m][n] = __builtin_amdgcn_mfma_f32_16x16x32_bf16(Bt[n][k], At[m][k], acc[ai][bj][m][n], 0, 0, 0); __builtin_amdgcn_s_setprio(0); } while (0)
; #define PG8_WAIT_V(n) asm volatile("s_waitcnt vmcnt(" #n ")" ::: "memory")
; #define PG8_WAIT_L(n) asm volatile("s_waitcnt lgkmcnt(" #n ")" ::: "memory")
; #define PG8_BAR __builtin_amdgcn_s_barrier()
; #define PG8_SCHED __builtin_amdgcn_sched_barrier(0)
; template <class Epi>
; __device__ __forceinline__ void gemm_phase(LAS unsigned char* lds, const Gemm g, const StaticOrder& S, const Epi& E) {
;     ...
;             PG8_WAIT_L(8); PG8_BAR; PG8_WAIT_L(0); PG8_MMA(0, 0, At, B0); PG8_BAR; PG8_SCHED;
;             PG8_LDB(B1, 1, 1); PG8_STAGE(PG8_SB(1, 0), b3, voffB);
;             PG8_BAR; PG8_WAIT_L(0); PG8_MMA(0, 1, At, B1); PG8_BAR;
;             PG8_LDA(At, 1, 1); PG8_STAGE(PG8_SA(1, 0), a3, voffA);
;             PG8_BAR; PG8_WAIT_L(0); PG8_MMA(1, 0, At, B0); PG8_BAR; PG8_SCHED;
;             PG8_STAGE(PG8_SB(1, 1), b3 + hstepB, voffB);
;             PG8_WAIT_V(6); PG8_BAR; PG8_MMA(1, 1, At, B1); PG8_BAR;
	s_waitcnt lgkmcnt(3)
	v_mfma_f32_16x16x32_bf16 v[116:119], v[194:197], v[144:147], v[116:119]
	s_setprio 1
	s_waitcnt lgkmcnt(1)
	v_mfma_f32_16x16x32_bf16 v[112:115], v[202:205], v[144:147], v[112:115]
	s_mov_b32 m0, s29
	v_lshl_add_u64 v[210:211], s[16:17], 0, v[156:157]
	v_mfma_f32_16x16x32_bf16 v[100:103], v[194:197], v[166:169], v[100:103]
	v_mfma_f32_16x16x32_bf16 v[96:99], v[202:205], v[166:169], v[96:99]
	v_mfma_f32_16x16x32_bf16 v[84:87], v[194:197], v[178:181], v[84:87]
	v_mfma_f32_16x16x32_bf16 v[80:83], v[202:205], v[178:181], v[80:83]
	v_mfma_f32_16x16x32_bf16 v[68:71], v[194:197], v[186:189], v[68:71]
	v_mfma_f32_16x16x32_bf16 v[64:67], v[202:205], v[186:189], v[64:67]
	v_mfma_f32_16x16x32_bf16 v[116:119], v[198:201], v[148:151], v[116:119]
	s_waitcnt lgkmcnt(0)
	v_mfma_f32_16x16x32_bf16 v[112:115], v[206:209], v[148:151], v[112:115]
	v_mfma_f32_16x16x32_bf16 v[100:103], v[198:201], v[174:177], v[100:103]
	v_mfma_f32_16x16x32_bf16 v[96:99], v[206:209], v[174:177], v[96:99]
	v_mfma_f32_16x16x32_bf16 v[84:87], v[198:201], v[182:185], v[84:87]
	v_mfma_f32_16x16x32_bf16 v[80:83], v[206:209], v[182:185], v[80:83]
	v_mfma_f32_16x16x32_bf16 v[68:71], v[198:201], v[190:193], v[68:71]
	s_setprio 0
	v_mfma_f32_16x16x32_bf16 v[64:67], v[206:209], v[190:193], v[64:67]
	s_barrier
	ds_read_b128 v[144:147], v172 offset:49152
	ds_read_b128 v[148:151], v172 offset:50176
	ds_read_b128 v[166:169], v172 offset:51200
	ds_read_b128 v[174:177], v172 offset:52224
	ds_read_b128 v[178:181], v172 offset:53248
	ds_read_b128 v[182:185], v172 offset:54272
	ds_read_b128 v[186:189], v172 offset:55296
	ds_read_b128 v[190:193], v172 offset:56320
	global_load_lds_dwordx4 v[210:211], off
	s_mov_b32 m0, s30
	v_lshl_add_u64 v[210:211], s[16:17], 0, v[158:159]
	global_load_lds_dwordx4 v[210:211], off
	s_barrier
	s_waitcnt lgkmcnt(7)
	v_mfma_f32_16x16x32_bf16 v[60:63], v[128:131], v[144:147], v[60:63]
	s_setprio 1
	v_mfma_f32_16x16x32_bf16 v[56:59], v[136:139], v[144:147], v[56:59]
	s_waitcnt lgkmcnt(5)
	v_mfma_f32_16x16x32_bf16 v[44:47], v[128:131], v[166:169], v[44:47]
	v_mfma_f32_16x16x32_bf16 v[40:43], v[136:139], v[166:169], v[40:43]
	s_waitcnt lgkmcnt(3)
	v_mfma_f32_16x16x32_bf16 v[28:31], v[128:131], v[178:181], v[28:31]
	v_mfma_f32_16x16x32_bf16 v[24:27], v[136:139], v[178:181], v[24:27]
	s_waitcnt lgkmcnt(1)
	v_mfma_f32_16x16x32_bf16 v[12:15], v[128:131], v[186:189], v[12:15]
	v_mfma_f32_16x16x32_bf16 v[8:11], v[136:139], v[186:189], v[8:11]
	v_mfma_f32_16x16x32_bf16 v[60:63], v[132:135], v[148:151], v[60:63]
	v_mfma_f32_16x16x32_bf16 v[56:59], v[140:143], v[148:151], v[56:59]
	v_mfma_f32_16x16x32_bf16 v[44:47], v[132:135], v[174:177], v[44:47]
	v_mfma_f32_16x16x32_bf16 v[40:43], v[140:143], v[174:177], v[40:43]
	v_mfma_f32_16x16x32_bf16 v[28:31], v[132:135], v[182:185], v[28:31]
	v_mfma_f32_16x16x32_bf16 v[24:27], v[140:143], v[182:185], v[24:27]
	s_waitcnt lgkmcnt(0)
	v_mfma_f32_16x16x32_bf16 v[12:15], v[132:135], v[190:193], v[12:15]
	s_setprio 0
	v_mfma_f32_16x16x32_bf16 v[8:11], v[140:143], v[190:193], v[8:11]
	s_barrier
	s_add_u32 s14, s14, 0x84000
	s_addc_u32 s15, s15, 0
	s_add_i32 s16, s40, s23
	s_mov_b32 m0, s16
	v_lshl_add_u64 v[128:129], s[14:15], 0, v[156:157]
	global_load_lds_dwordx4 v[128:129], off
	s_add_i32 m0, s16, 0x2000
	v_lshl_add_u64 v[128:129], s[14:15], 0, v[158:159]
	global_load_lds_dwordx4 v[128:129], off
	s_waitcnt vmcnt(6)
	s_barrier
	v_mfma_f32_16x16x32_bf16 v[52:55], v[194:197], v[144:147], v[52:55]
	s_setprio 1
	v_mfma_f32_16x16x32_bf16 v[48:51], v[202:205], v[144:147], v[48:51]
	s_add_i32 s38, s38, 2
	s_add_u32 s12, s12, 0x8000
	s_addc_u32 s13, s13, 0
	s_add_u32 s36, s36, 0x8000
	s_addc_u32 s37, s37, 0
	v_mfma_f32_16x16x32_bf16 v[36:39], v[194:197], v[166:169], v[36:39]
	v_mfma_f32_16x16x32_bf16 v[32:35], v[202:205], v[166:169], v[32:35]
	v_mfma_f32_16x16x32_bf16 v[20:23], v[194:197], v[178:181], v[20:23]
	v_mfma_f32_16x16x32_bf16 v[16:19], v[202:205], v[178:181], v[16:19]
	v_mfma_f32_16x16x32_bf16 v[4:7], v[194:197], v[186:189], v[4:7]
	v_mfma_f32_16x16x32_bf16 v[0:3], v[202:205], v[186:189], v[0:3]
	v_mfma_f32_16x16x32_bf16 v[52:55], v[198:201], v[148:151], v[52:55]
	v_mfma_f32_16x16x32_bf16 v[48:51], v[206:209], v[148:151], v[48:51]
	v_mfma_f32_16x16x32_bf16 v[36:39], v[198:201], v[174:177], v[36:39]
	v_mfma_f32_16x16x32_bf16 v[32:35], v[206:209], v[174:177], v[32:35]
	v_mfma_f32_16x16x32_bf16 v[20:23], v[198:201], v[182:185], v[20:23]
	v_mfma_f32_16x16x32_bf16 v[16:19], v[206:209], v[182:185], v[16:19]
	v_mfma_f32_16x16x32_bf16 v[4:7], v[198:201], v[190:193], v[4:7]
	s_cmp_gt_u32 s38, 29
	s_setprio 0
	v_mfma_f32_16x16x32_bf16 v[0:3], v[206:209], v[190:193], v[0:3]
	s_barrier
	s_cbranch_scc0 .LBB0_247
	s_branch .Lpeel_done_247
; #define PG8_STAGE(bufoff, gbase, voff) do { _Pragma("unroll") for (int _i = 0; _i < 2; ++_i) \
;         __builtin_amdgcn_global_load_lds((const unsigned*)((const char*)(gbase) + (voff)[_i]), (LAS unsigned*)(lds + (bufoff) + ldsw + _i * 8192), 16, 0, 0); } while (0)
; #define PG8_LDA(dst, b, h) do { _Pragma("unroll") for (int m = 0; m < 4; ++m) _Pragma("unroll") for (int k = 0; k < 2; ++k) dst[m][k] = *(const LAS bf16x8*)(lds + PG8_SA(b, h) + aoff + m * 2048 + k * 1024); } while (0)
; #define PG8_LDB(dst, b, h) do { _Pragma("unroll") for (int n = 0; n < 2; ++n) _Pragma("unroll") for (int k = 0; k < 2; ++k) dst[n][k] = *(const LAS bf16x8*)(lds + PG8_SB(b, h) + boff + n * 2048 + k * 1024); } while (0)
; #define PG8_WAIT_V(n) asm volatile("s_waitcnt vmcnt(" #n ")" ::: "memory")
; #define PG8_WAIT_L(n) asm volatile("s_waitcnt lgkmcnt(" #n ")" ::: "memory")
; #define PG8_BAR __builtin_amdgcn_s_barrier()
; template <class Epi>
; __device__ __forceinline__ void gemm_phase(LAS unsigned char* lds, const Gemm g, const StaticOrder& S, const Epi& E) {
;     ...
;         for (int t = 0; t < nt; t += 2) {
;             const bool last = (t == nt - 2);
;             const char* a1 = cA + (size_t)(t + 1) * kstep;
;             const char* a2 = last ? nA : cA + (size_t)(t + 2) * kstep; const char* b2 = last ? nB : cB + (size_t)(t + 2) * kstep;
;             const char* a3 = a2 + kstep; const char* b3 = b2 + kstep;
;             PG8_LDB(B0, 0, 0); PG8_SCHED; PG8_LDA(At, 0, 0); PG8_STAGE(PG8_SA(1, 1), a1 + hstepA, voffA);
;             PG8_WAIT_L(8); PG8_BAR; PG8_WAIT_L(0); PG8_MMA(0, 0, At, B0); PG8_BAR; PG8_SCHED;
;             PG8_LDB(B1, 0, 1); PG8_STAGE(PG8_SB(0, 0), b2, voffB);
;             PG8_BAR; PG8_WAIT_L(0); PG8_MMA(0, 1, At, B1); PG8_BAR;
;             PG8_LDA(At, 0, 1); PG8_STAGE(PG8_SA(0, 0), a2, voffA);
;             PG8_BAR; PG8_WAIT_L(0); PG8_MMA(1, 0, At, B0); PG8_BAR; PG8_SCHED;
;             PG8_STAGE(PG8_SB(0, 1), b2 + hstepB, voffB);
;             PG8_WAIT_V(6); PG8_BAR; PG8_MMA(1, 1, At, B1); PG8_BAR;
;             PG8_LDB(B0, 1, 0); PG8_SCHED; PG8_LDA(At, 1, 0); PG8_STAGE(PG8_SA(0, 1), a2 + hstepA, voffA);
;             PG8_WAIT_L(8); PG8_BAR; PG8_WAIT_L(0); PG8_MMA(0, 0, At, B0); PG8_BAR; PG8_SCHED;
;             PG8_LDB(B1, 1, 1); PG8_STAGE(PG8_SB(1, 0), b3, voffB);
;             PG8_BAR; PG8_WAIT_L(0); PG8_MMA(0, 1, At, B1); PG8_BAR;
.LBB0_247:
	s_add_u32 s14, s12, 0xfff84000
	s_addc_u32 s15, s13, -1
	s_cmp_eq_u32 s38, 28
	s_cselect_b32 s18, s11, s14
	s_cselect_b32 s19, s5, s15
	s_cselect_b32 s14, s35, s36
	s_cselect_b32 s15, s3, s37
	s_add_u32 s16, s18, 0x4000
	s_addc_u32 s17, s19, 0
	s_add_i32 s39, 0, 0x10000
	v_add_u32_e32 v140, s39, v170
	ds_read_b128 v[128:131], v140
	ds_read_b128 v[132:135], v140 offset:1024
	ds_read_b128 v[136:139], v140 offset:2048
	ds_read_b128 v[140:143], v140 offset:3072
	v_lshl_add_u64 v[194:195], s[12:13], 0, v[156:157]
	s_add_i32 m0, s25, 0xc000
	ds_read_b128 v[144:147], v172
	ds_read_b128 v[148:151], v172 offset:1024
	ds_read_b128 v[166:169], v172 offset:2048
	ds_read_b128 v[174:177], v172 offset:3072
	ds_read_b128 v[178:181], v172 offset:4096
	ds_read_b128 v[182:185], v172 offset:5120
	ds_read_b128 v[186:189], v172 offset:6144
	ds_read_b128 v[190:193], v172 offset:7168
	global_load_lds_dwordx4 v[194:195], off
	s_add_i32 m0, s25, 0xe000
	v_lshl_add_u64 v[194:195], s[12:13], 0, v[158:159]
	global_load_lds_dwordx4 v[194:195], off
	s_waitcnt lgkmcnt(8)
	s_barrier
	s_waitcnt lgkmcnt(7)
	v_mfma_f32_16x16x32_bf16 v[124:127], v[128:131], v[144:147], v[124:127]
	s_setprio 1
	v_mfma_f32_16x16x32_bf16 v[120:123], v[136:139], v[144:147], v[120:123]
	s_waitcnt lgkmcnt(5)
	v_mfma_f32_16x16x32_bf16 v[108:111], v[128:131], v[166:169], v[108:111]
	v_mfma_f32_16x16x32_bf16 v[104:107], v[136:139], v[166:169], v[104:107]
	s_waitcnt lgkmcnt(3)
	v_mfma_f32_16x16x32_bf16 v[92:95], v[128:131], v[178:181], v[92:95]
	v_mfma_f32_16x16x32_bf16 v[88:91], v[136:139], v[178:181], v[88:91]
	s_waitcnt lgkmcnt(1)
	v_mfma_f32_16x16x32_bf16 v[76:79], v[128:131], v[186:189], v[76:79]
	v_mfma_f32_16x16x32_bf16 v[72:75], v[136:139], v[186:189], v[72:75]
	v_mfma_f32_16x16x32_bf16 v[124:127], v[132:135], v[148:151], v[124:127]
	v_mfma_f32_16x16x32_bf16 v[120:123], v[140:143], v[148:151], v[120:123]
	v_mfma_f32_16x16x32_bf16 v[108:111], v[132:135], v[174:177], v[108:111]
	v_mfma_f32_16x16x32_bf16 v[104:107], v[140:143], v[174:177], v[104:107]
	v_mfma_f32_16x16x32_bf16 v[92:95], v[132:135], v[182:185], v[92:95]
	v_mfma_f32_16x16x32_bf16 v[88:91], v[140:143], v[182:185], v[88:91]
	s_waitcnt lgkmcnt(0)
	v_mfma_f32_16x16x32_bf16 v[76:79], v[132:135], v[190:193], v[76:79]
	s_setprio 0
	v_mfma_f32_16x16x32_bf16 v[72:75], v[140:143], v[190:193], v[72:75]
	s_barrier
	s_add_i32 s42, 0, 0x14000
	s_add_i32 s39, s39, s23
	v_add_u32_e32 v152, s42, v170
	v_lshl_add_u64 v[210:211], s[14:15], 0, v[156:157]
	s_mov_b32 m0, s39
	ds_read_b128 v[194:197], v152
	ds_read_b128 v[198:201], v152 offset:1024
	ds_read_b128 v[202:205], v152 offset:2048
	ds_read_b128 v[206:209], v152 offset:3072
	global_load_lds_dwordx4 v[210:211], off
	s_add_i32 m0, s39, 0x2000
	v_lshl_add_u64 v[210:211], s[14:15], 0, v[158:159]
	global_load_lds_dwordx4 v[210:211], off
	s_barrier
	s_waitcnt lgkmcnt(3)
	v_mfma_f32_16x16x32_bf16 v[116:119], v[194:197], v[144:147], v[116:119]
	s_setprio 1
	s_waitcnt lgkmcnt(1)
	v_mfma_f32_16x16x32_bf16 v[112:115], v[202:205], v[144:147], v[112:115]
	s_mov_b32 m0, s25
	v_lshl_add_u64 v[210:211], s[18:19], 0, v[156:157]
	v_mfma_f32_16x16x32_bf16 v[100:103], v[194:197], v[166:169], v[100:103]
	v_mfma_f32_16x16x32_bf16 v[96:99], v[202:205], v[166:169], v[96:99]
	v_mfma_f32_16x16x32_bf16 v[84:87], v[194:197], v[178:181], v[84:87]
	v_mfma_f32_16x16x32_bf16 v[80:83], v[202:205], v[178:181], v[80:83]
	v_mfma_f32_16x16x32_bf16 v[68:71], v[194:197], v[186:189], v[68:71]
	v_mfma_f32_16x16x32_bf16 v[64:67], v[202:205], v[186:189], v[64:67]
	v_mfma_f32_16x16x32_bf16 v[116:119], v[198:201], v[148:151], v[116:119]
	s_waitcnt lgkmcnt(0)
	v_mfma_f32_16x16x32_bf16 v[112:115], v[206:209], v[148:151], v[112:115]
	v_mfma_f32_16x16x32_bf16 v[100:103], v[198:201], v[174:177], v[100:103]
	v_mfma_f32_16x16x32_bf16 v[96:99], v[206:209], v[174:177], v[96:99]
	v_mfma_f32_16x16x32_bf16 v[84:87], v[198:201], v[182:185], v[84:87]
	v_mfma_f32_16x16x32_bf16 v[80:83], v[206:209], v[182:185], v[80:83]
	v_mfma_f32_16x16x32_bf16 v[68:71], v[198:201], v[190:193], v[68:71]
	s_setprio 0
	v_mfma_f32_16x16x32_bf16 v[64:67], v[206:209], v[190:193], v[64:67]
	s_barrier
	ds_read_b128 v[144:147], v172 offset:16384
	ds_read_b128 v[148:151], v172 offset:17408
	ds_read_b128 v[166:169], v172 offset:18432
	ds_read_b128 v[174:177], v172 offset:19456
	ds_read_b128 v[178:181], v172 offset:20480
	ds_read_b128 v[182:185], v172 offset:21504
	ds_read_b128 v[186:189], v172 offset:22528
	ds_read_b128 v[190:193], v172 offset:23552
	global_load_lds_dwordx4 v[210:211], off
	s_mov_b32 m0, s26
	v_lshl_add_u64 v[210:211], s[18:19], 0, v[158:159]
	global_load_lds_dwordx4 v[210:211], off
	s_barrier
	s_waitcnt lgkmcnt(7)
	v_mfma_f32_16x16x32_bf16 v[60:63], v[128:131], v[144:147], v[60:63]
	s_setprio 1
	v_mfma_f32_16x16x32_bf16 v[56:59], v[136:139], v[144:147], v[56:59]
	s_waitcnt lgkmcnt(5)
	v_mfma_f32_16x16x32_bf16 v[44:47], v[128:131], v[166:169], v[44:47]
	v_mfma_f32_16x16x32_bf16 v[40:43], v[136:139], v[166:169], v[40:43]
	s_waitcnt lgkmcnt(3)
	v_mfma_f32_16x16x32_bf16 v[28:31], v[128:131], v[178:181], v[28:31]
	v_mfma_f32_16x16x32_bf16 v[24:27], v[136:139], v[178:181], v[24:27]
	s_waitcnt lgkmcnt(1)
	v_mfma_f32_16x16x32_bf16 v[12:15], v[128:131], v[186:189], v[12:15]
	v_mfma_f32_16x16x32_bf16 v[8:11], v[136:139], v[186:189], v[8:11]
	v_mfma_f32_16x16x32_bf16 v[60:63], v[132:135], v[148:151], v[60:63]
	v_mfma_f32_16x16x32_bf16 v[56:59], v[140:143], v[148:151], v[56:59]
	v_mfma_f32_16x16x32_bf16 v[44:47], v[132:135], v[174:177], v[44:47]
	v_mfma_f32_16x16x32_bf16 v[40:43], v[140:143], v[174:177], v[40:43]
	v_mfma_f32_16x16x32_bf16 v[28:31], v[132:135], v[182:185], v[28:31]
	v_mfma_f32_16x16x32_bf16 v[24:27], v[140:143], v[182:185], v[24:27]
	s_waitcnt lgkmcnt(0)
	v_mfma_f32_16x16x32_bf16 v[12:15], v[132:135], v[190:193], v[12:15]
	s_setprio 0
	v_mfma_f32_16x16x32_bf16 v[8:11], v[140:143], v[190:193], v[8:11]
	s_barrier
; #define PG8_STAGE(bufoff, gbase, voff) do { _Pragma("unroll") for (int _i = 0; _i < 2; ++_i) \
;         __builtin_amdgcn_global_load_lds((const unsigned*)((const char*)(gbase) + (voff)[_i]), (LAS unsigned*)(lds + (bufoff) + ldsw + _i * 8192), 16, 0, 0); } while (0)
; #define PG8_LDA(dst, b, h) do { _Pragma("unroll") for (int m = 0; m < 4; ++m) _Pragma("unroll") for (int k = 0; k < 2; ++k) dst[m][k] = *(const LAS bf16x8*)(lds + PG8_SA(b, h) + aoff + m * 2048 + k * 1024); } while (0)
; #define PG8_LDB(dst, b, h) do { _Pragma("unroll") for (int n = 0; n < 2; ++n) _Pragma("unroll") for (int k = 0; k < 2; ++k) dst[n][k] = *(const LAS bf16x8*)(lds + PG8_SB(b, h) + boff + n * 2048 + k * 1024); } while (0)
; #define PG8_MMA(ai, bj, At, Bt) do { __builtin_amdgcn_s_setprio(1); _Pragma("unroll") for (int m = 0; m < 4; ++m) _Pragma("unroll") for (int n = 0; n < 2; ++n) _Pragma("unroll") for (int k = 0; k < 2; ++k) \
;         acc[ai][bj][m][n] = __builtin_amdgcn_mfma_f32_16x16x32_bf16(Bt[n][k], At[m][k], acc[ai][bj][m][n], 0, 0, 0); __builtin_amdgcn_s_setprio(0); } while (0)
; #define PG8_WAIT_V(n) asm volatile("s_waitcnt vmcnt(" #n ")" ::: "memory")
; #define PG8_WAIT_L(n) asm volatile("s_waitcnt lgkmcnt(" #n ")" ::: "memory")
; #define PG8_BAR __builtin_amdgcn_s_barrier()
; #define PG8_SCHED __builtin_amdgcn_sched_barrier(0)
; template <class Epi>
; __device__ __forceinline__ void gemm_phase(LAS unsigned char* lds, const Gemm g, const StaticOrder& S, const Epi& E) {
;     ...
;             PG8_STAGE(PG8_SB(0, 1), b2 + hstepB, voffB);
;             PG8_WAIT_V(6); PG8_BAR; PG8_MMA(1, 1, At, B1); PG8_BAR;
;             PG8_LDB(B0, 1, 0); PG8_SCHED; PG8_LDA(At, 1, 0); PG8_STAGE(PG8_SA(0, 1), a2 + hstepA, voffA);
;             PG8_WAIT_L(8); PG8_BAR; PG8_WAIT_L(0); PG8_MMA(0, 0, At, B0); PG8_BAR; PG8_SCHED;
;             PG8_LDB(B1, 1, 1); PG8_STAGE(PG8_SB(1, 0), b3, voffB);
;             PG8_BAR; PG8_WAIT_L(0); PG8_MMA(0, 1, At, B1); PG8_BAR;
	s_add_u32 s40, s14, 0x80000
	s_addc_u32 s41, s15, 0
	s_add_i32 s39, s42, s23
	s_mov_b32 m0, s39
	v_lshl_add_u64 v[128:129], s[40:41], 0, v[156:157]
	global_load_lds_dwordx4 v[128:129], off
	s_add_i32 m0, s39, 0x2000
	v_lshl_add_u64 v[128:129], s[40:41], 0, v[158:159]
	global_load_lds_dwordx4 v[128:129], off
	s_waitcnt vmcnt(6)
	s_barrier
	v_mfma_f32_16x16x32_bf16 v[52:55], v[194:197], v[144:147], v[52:55]
	s_setprio 1
	v_mfma_f32_16x16x32_bf16 v[48:51], v[202:205], v[144:147], v[48:51]
	s_add_i32 s39, 0, 0x18000
	v_add_u32_e32 v140, s39, v170
	v_mfma_f32_16x16x32_bf16 v[36:39], v[194:197], v[166:169], v[36:39]
	v_mfma_f32_16x16x32_bf16 v[32:35], v[202:205], v[166:169], v[32:35]
	v_mfma_f32_16x16x32_bf16 v[20:23], v[194:197], v[178:181], v[20:23]
	v_mfma_f32_16x16x32_bf16 v[16:19], v[202:205], v[178:181], v[16:19]
	v_mfma_f32_16x16x32_bf16 v[4:7], v[194:197], v[186:189], v[4:7]
	v_mfma_f32_16x16x32_bf16 v[0:3], v[202:205], v[186:189], v[0:3]
	v_mfma_f32_16x16x32_bf16 v[52:55], v[198:201], v[148:151], v[52:55]
	v_mfma_f32_16x16x32_bf16 v[48:51], v[206:209], v[148:151], v[48:51]
	v_mfma_f32_16x16x32_bf16 v[36:39], v[198:201], v[174:177], v[36:39]
	v_mfma_f32_16x16x32_bf16 v[32:35], v[206:209], v[174:177], v[32:35]
	v_mfma_f32_16x16x32_bf16 v[20:23], v[198:201], v[182:185], v[20:23]
	v_mfma_f32_16x16x32_bf16 v[16:19], v[206:209], v[182:185], v[16:19]
	v_mfma_f32_16x16x32_bf16 v[4:7], v[198:201], v[190:193], v[4:7]
	s_setprio 0
	v_mfma_f32_16x16x32_bf16 v[0:3], v[206:209], v[190:193], v[0:3]
	s_barrier
	ds_read_b128 v[128:131], v140
	ds_read_b128 v[132:135], v140 offset:1024
	ds_read_b128 v[136:139], v140 offset:2048
	ds_read_b128 v[140:143], v140 offset:3072
	s_add_u32 s18, s18, 0x80000
	s_addc_u32 s19, s19, 0
	s_mov_b32 m0, s27
	v_lshl_add_u64 v[194:195], s[18:19], 0, v[156:157]
	ds_read_b128 v[144:147], v172 offset:32768
	ds_read_b128 v[148:151], v172 offset:33792
	ds_read_b128 v[166:169], v172 offset:34816
	ds_read_b128 v[174:177], v172 offset:35840
	ds_read_b128 v[178:181], v172 offset:36864
	ds_read_b128 v[182:185], v172 offset:37888
	ds_read_b128 v[186:189], v172 offset:38912
	ds_read_b128 v[190:193], v172 offset:39936
	global_load_lds_dwordx4 v[194:195], off
	s_mov_b32 m0, s28
	v_lshl_add_u64 v[194:195], s[18:19], 0, v[158:159]
	global_load_lds_dwordx4 v[194:195], off
	s_waitcnt lgkmcnt(8)
	s_barrier
	s_waitcnt lgkmcnt(7)
	v_mfma_f32_16x16x32_bf16 v[124:127], v[128:131], v[144:147], v[124:127]
	s_setprio 1
	v_mfma_f32_16x16x32_bf16 v[120:123], v[136:139], v[144:147], v[120:123]
	s_waitcnt lgkmcnt(5)
	v_mfma_f32_16x16x32_bf16 v[108:111], v[128:131], v[166:169], v[108:111]
	v_mfma_f32_16x16x32_bf16 v[104:107], v[136:139], v[166:169], v[104:107]
	s_waitcnt lgkmcnt(3)
	v_mfma_f32_16x16x32_bf16 v[92:95], v[128:131], v[178:181], v[92:95]
	v_mfma_f32_16x16x32_bf16 v[88:91], v[136:139], v[178:181], v[88:91]
	s_waitcnt lgkmcnt(1)
	v_mfma_f32_16x16x32_bf16 v[76:79], v[128:131], v[186:189], v[76:79]
	v_mfma_f32_16x16x32_bf16 v[72:75], v[136:139], v[186:189], v[72:75]
	v_mfma_f32_16x16x32_bf16 v[124:127], v[132:135], v[148:151], v[124:127]
	v_mfma_f32_16x16x32_bf16 v[120:123], v[140:143], v[148:151], v[120:123]
	v_mfma_f32_16x16x32_bf16 v[108:111], v[132:135], v[174:177], v[108:111]
	v_mfma_f32_16x16x32_bf16 v[104:107], v[140:143], v[174:177], v[104:107]
	v_mfma_f32_16x16x32_bf16 v[92:95], v[132:135], v[182:185], v[92:95]
	v_mfma_f32_16x16x32_bf16 v[88:91], v[140:143], v[182:185], v[88:91]
	s_waitcnt lgkmcnt(0)
	v_mfma_f32_16x16x32_bf16 v[76:79], v[132:135], v[190:193], v[76:79]
	s_setprio 0
	v_mfma_f32_16x16x32_bf16 v[72:75], v[140:143], v[190:193], v[72:75]
	s_barrier
	s_add_i32 s40, 0, 0x1c000
	s_add_u32 s18, s14, 0x4000
	s_addc_u32 s19, s15, 0
	s_add_i32 s39, s39, s23
	v_add_u32_e32 v152, s40, v170
	v_lshl_add_u64 v[210:211], s[18:19], 0, v[156:157]
	s_mov_b32 m0, s39
	ds_read_b128 v[194:197], v152
	ds_read_b128 v[198:201], v152 offset:1024
	ds_read_b128 v[202:205], v152 offset:2048
	ds_read_b128 v[206:209], v152 offset:3072
	global_load_lds_dwordx4 v[210:211], off
	s_add_i32 m0, s39, 0x2000
	v_lshl_add_u64 v[210:211], s[18:19], 0, v[158:159]
	global_load_lds_dwordx4 v[210:211], off
	s_barrier
; #define PG8_STAGE(bufoff, gbase, voff) do { _Pragma("unroll") for (int _i = 0; _i < 2; ++_i) \
;         __builtin_amdgcn_global_load_lds((const unsigned*)((const char*)(gbase) + (voff)[_i]), (LAS unsigned*)(lds + (bufoff) + ldsw + _i * 8192), 16, 0, 0); } while (0)
; #define PG8_LDA(dst, b, h) do { _Pragma("unroll") for (int m = 0; m < 4; ++m) _Pragma("unroll") for (int k = 0; k < 2; ++k) dst[m][k] = *(const LAS bf16x8*)(lds + PG8_SA(b, h) + aoff + m * 2048 + k * 1024); } while (0)
; #define PG8_MMA(ai, bj, At, Bt) do { __builtin_amdgcn_s_setprio(1); _Pragma("unroll") for (int m = 0; m < 4; ++m) _Pragma("unroll") for (int n = 0; n < 2; ++n) _Pragma("unroll") for (int k = 0; k < 2; ++k) \
;         acc[ai][bj][m][n] = __builtin_amdgcn_mfma_f32_16x16x32_bf16(Bt[n][k], At[m][k], acc[ai][bj][m][n], 0, 0, 0); __builtin_amdgcn_s_setprio(0); } while (0)
; #define PG8_WAIT_V(n) asm volatile("s_waitcnt vmcnt(" #n ")" ::: "memory")
; #define PG8_WAIT_L(n) asm volatile("s_waitcnt lgkmcnt(" #n ")" ::: "memory")
; #define PG8_BAR __builtin_amdgcn_s_barrier()
; #define PG8_SCHED __builtin_amdgcn_sched_barrier(0)
; template <class Epi>
; __device__ __forceinline__ void gemm_phase(LAS unsigned char* lds, const Gemm g, const StaticOrder& S, const Epi& E) {
;     ...
;             PG8_BAR; PG8_WAIT_L(0); PG8_MMA(0, 1, At, B1); PG8_BAR;
;             PG8_LDA(At, 1, 1); PG8_STAGE(PG8_SA(1, 0), a3, voffA);
;             PG8_BAR; PG8_WAIT_L(0); PG8_MMA(1, 0, At, B0); PG8_BAR; PG8_SCHED;
;             PG8_STAGE(PG8_SB(1, 1), b3 + hstepB, voffB);
;             PG8_WAIT_V(6); PG8_BAR; PG8_MMA(1, 1, At, B1); PG8_BAR;
;         }
	s_waitcnt lgkmcnt(3)
	v_mfma_f32_16x16x32_bf16 v[116:119], v[194:197], v[144:147], v[116:119]
	s_setprio 1
	s_waitcnt lgkmcnt(1)
	v_mfma_f32_16x16x32_bf16 v[112:115], v[202:205], v[144:147], v[112:115]
	s_mov_b32 m0, s29
	v_lshl_add_u64 v[210:211], s[16:17], 0, v[156:157]
	v_mfma_f32_16x16x32_bf16 v[100:103], v[194:197], v[166:169], v[100:103]
	v_mfma_f32_16x16x32_bf16 v[96:99], v[202:205], v[166:169], v[96:99]
	v_mfma_f32_16x16x32_bf16 v[84:87], v[194:197], v[178:181], v[84:87]
	v_mfma_f32_16x16x32_bf16 v[80:83], v[202:205], v[178:181], v[80:83]
	v_mfma_f32_16x16x32_bf16 v[68:71], v[194:197], v[186:189], v[68:71]
	v_mfma_f32_16x16x32_bf16 v[64:67], v[202:205], v[186:189], v[64:67]
	v_mfma_f32_16x16x32_bf16 v[116:119], v[198:201], v[148:151], v[116:119]
	s_waitcnt lgkmcnt(0)
	v_mfma_f32_16x16x32_bf16 v[112:115], v[206:209], v[148:151], v[112:115]
	v_mfma_f32_16x16x32_bf16 v[100:103], v[198:201], v[174:177], v[100:103]
	v_mfma_f32_16x16x32_bf16 v[96:99], v[206:209], v[174:177], v[96:99]
	v_mfma_f32_16x16x32_bf16 v[84:87], v[198:201], v[182:185], v[84:87]
	v_mfma_f32_16x16x32_bf16 v[80:83], v[206:209], v[182:185], v[80:83]
	v_mfma_f32_16x16x32_bf16 v[68:71], v[198:201], v[190:193], v[68:71]
	s_setprio 0
	v_mfma_f32_16x16x32_bf16 v[64:67], v[206:209], v[190:193], v[64:67]
	s_barrier
	ds_read_b128 v[144:147], v172 offset:49152
	ds_read_b128 v[148:151], v172 offset:50176
	ds_read_b128 v[166:169], v172 offset:51200
	ds_read_b128 v[174:177], v172 offset:52224
	ds_read_b128 v[178:181], v172 offset:53248
	ds_read_b128 v[182:185], v172 offset:54272
	ds_read_b128 v[186:189], v172 offset:55296
	ds_read_b128 v[190:193], v172 offset:56320
	global_load_lds_dwordx4 v[210:211], off
	s_mov_b32 m0, s30
	v_lshl_add_u64 v[210:211], s[16:17], 0, v[158:159]
	global_load_lds_dwordx4 v[210:211], off
	s_barrier
	s_waitcnt lgkmcnt(7)
	v_mfma_f32_16x16x32_bf16 v[60:63], v[128:131], v[144:147], v[60:63]
	s_setprio 1
	v_mfma_f32_16x16x32_bf16 v[56:59], v[136:139], v[144:147], v[56:59]
	s_waitcnt lgkmcnt(5)
	v_mfma_f32_16x16x32_bf16 v[44:47], v[128:131], v[166:169], v[44:47]
	v_mfma_f32_16x16x32_bf16 v[40:43], v[136:139], v[166:169], v[40:43]
	s_waitcnt lgkmcnt(3)
	v_mfma_f32_16x16x32_bf16 v[28:31], v[128:131], v[178:181], v[28:31]
	v_mfma_f32_16x16x32_bf16 v[24:27], v[136:139], v[178:181], v[24:27]
	s_waitcnt lgkmcnt(1)
	v_mfma_f32_16x16x32_bf16 v[12:15], v[128:131], v[186:189], v[12:15]
	v_mfma_f32_16x16x32_bf16 v[8:11], v[136:139], v[186:189], v[8:11]
	v_mfma_f32_16x16x32_bf16 v[60:63], v[132:135], v[148:151], v[60:63]
	v_mfma_f32_16x16x32_bf16 v[56:59], v[140:143], v[148:151], v[56:59]
	v_mfma_f32_16x16x32_bf16 v[44:47], v[132:135], v[174:177], v[44:47]
	v_mfma_f32_16x16x32_bf16 v[40:43], v[140:143], v[174:177], v[40:43]
	v_mfma_f32_16x16x32_bf16 v[28:31], v[132:135], v[182:185], v[28:31]
	v_mfma_f32_16x16x32_bf16 v[24:27], v[140:143], v[182:185], v[24:27]
	s_waitcnt lgkmcnt(0)
	v_mfma_f32_16x16x32_bf16 v[12:15], v[132:135], v[190:193], v[12:15]
	s_setprio 0
	v_mfma_f32_16x16x32_bf16 v[8:11], v[140:143], v[190:193], v[8:11]
	s_barrier
	s_add_u32 s14, s14, 0x84000
	s_addc_u32 s15, s15, 0
	s_add_i32 s16, s40, s23
	s_mov_b32 m0, s16
	v_lshl_add_u64 v[128:129], s[14:15], 0, v[156:157]
	global_load_lds_dwordx4 v[128:129], off
	s_add_i32 m0, s16, 0x2000
	v_lshl_add_u64 v[128:129], s[14:15], 0, v[158:159]
	global_load_lds_dwordx4 v[128:129], off
	s_waitcnt vmcnt(6)
	s_barrier
	v_mfma_f32_16x16x32_bf16 v[52:55], v[194:197], v[144:147], v[52:55]
	s_setprio 1
	v_mfma_f32_16x16x32_bf16 v[48:51], v[202:205], v[144:147], v[48:51]
	s_add_i32 s38, s38, 2
	s_add_u32 s12, s12, 0x8000
	s_addc_u32 s13, s13, 0
	s_add_u32 s36, s36, 0x8000
	s_addc_u32 s37, s37, 0
	v_mfma_f32_16x16x32_bf16 v[36:39], v[194:197], v[166:169], v[36:39]
	v_mfma_f32_16x16x32_bf16 v[32:35], v[202:205], v[166:169], v[32:35]
	v_mfma_f32_16x16x32_bf16 v[20:23], v[194:197], v[178:181], v[20:23]
	v_mfma_f32_16x16x32_bf16 v[16:19], v[202:205], v[178:181], v[16:19]
	v_mfma_f32_16x16x32_bf16 v[4:7], v[194:197], v[186:189], v[4:7]
	v_mfma_f32_16x16x32_bf16 v[0:3], v[202:205], v[186:189], v[0:3]
	v_mfma_f32_16x16x32_bf16 v[52:55], v[198:201], v[148:151], v[52:55]
	v_mfma_f32_16x16x32_bf16 v[48:51], v[206:209], v[148:151], v[48:51]
	v_mfma_f32_16x16x32_bf16 v[36:39], v[198:201], v[174:177], v[36:39]
	v_mfma_f32_16x16x32_bf16 v[32:35], v[206:209], v[174:177], v[32:35]
	v_mfma_f32_16x16x32_bf16 v[20:23], v[198:201], v[182:185], v[20:23]
	v_mfma_f32_16x16x32_bf16 v[16:19], v[206:209], v[182:185], v[16:19]
	v_mfma_f32_16x16x32_bf16 v[4:7], v[198:201], v[190:193], v[4:7]
	s_cmp_gt_u32 s38, 29
	s_setprio 0
	v_mfma_f32_16x16x32_bf16 v[0:3], v[206:209], v[190:193], v[0:3]
	s_barrier
	s_cbranch_scc0 .LBB0_247
